# GEMM loops: same-accumulator MFMA pairs back to back, s_setprio toggles removed
# speedup vs baseline: 1.0164x; 1.0055x over previous
.LBB0_200:
	ds_read_b128 v[148:151], v169
	ds_read_b128 v[152:155], v169 offset:1024
	ds_read_b128 v[156:159], v169 offset:2048
	ds_read_b128 v[160:163], v169 offset:3072
	ds_read_b128 v[174:177], v170
	ds_read_b128 v[178:181], v170 offset:1024
	ds_read_b128 v[182:185], v170 offset:2048
	ds_read_b128 v[186:189], v170 offset:3072
	s_add_u32 s26, s6, 0xfff00800
	s_addc_u32 s27, s7, -1
	s_cmp_eq_u32 s34, 60
	s_cselect_b32 s29, s17, s27
	s_cselect_b32 s28, s23, s26
	s_cselect_b32 s27, s15, s31
	s_cselect_b32 s26, s25, s30
	v_lshl_add_u64 v[190:191], s[6:7], 0, v[138:139]
	s_add_i32 m0, s41, 0xc000
	s_nop 0
	global_load_lds_dwordx4 v[190:191], off
	v_lshl_add_u64 v[190:191], s[6:7], 0, v[140:141]
	s_add_i32 m0, s41, 0xe000
	s_nop 0
	global_load_lds_dwordx4 v[190:191], off
	ds_read_b128 v[190:193], v171
	ds_read_b128 v[194:197], v171 offset:1024
	ds_read_b128 v[198:201], v171 offset:2048
	ds_read_b128 v[202:205], v171 offset:3072
	ds_read_b128 v[206:209], v171 offset:4096
	ds_read_b128 v[210:213], v171 offset:5120
	ds_read_b128 v[214:217], v171 offset:6144
	ds_read_b128 v[218:221], v171 offset:7168
	s_waitcnt vmcnt(8)
	s_waitcnt lgkmcnt(0)
	s_barrier
	s_waitcnt lgkmcnt(0)
	v_mfma_f32_16x16x32_bf16 v[124:127], v[148:151], v[190:193], v[124:127]
	v_mfma_f32_16x16x32_bf16 v[124:127], v[152:155], v[194:197], v[124:127]
	v_mfma_f32_16x16x32_bf16 v[120:123], v[156:159], v[190:193], v[120:123]
	v_mfma_f32_16x16x32_bf16 v[120:123], v[160:163], v[194:197], v[120:123]
	v_mfma_f32_16x16x32_bf16 v[116:119], v[148:151], v[198:201], v[116:119]
	v_mfma_f32_16x16x32_bf16 v[116:119], v[152:155], v[202:205], v[116:119]
	v_mfma_f32_16x16x32_bf16 v[112:115], v[156:159], v[198:201], v[112:115]
	v_mfma_f32_16x16x32_bf16 v[112:115], v[160:163], v[202:205], v[112:115]
	v_mfma_f32_16x16x32_bf16 v[108:111], v[148:151], v[206:209], v[108:111]
	v_mfma_f32_16x16x32_bf16 v[108:111], v[152:155], v[210:213], v[108:111]
	v_mfma_f32_16x16x32_bf16 v[104:107], v[156:159], v[206:209], v[104:107]
	v_mfma_f32_16x16x32_bf16 v[104:107], v[160:163], v[210:213], v[104:107]
	v_mfma_f32_16x16x32_bf16 v[100:103], v[148:151], v[214:217], v[100:103]
	v_mfma_f32_16x16x32_bf16 v[100:103], v[152:155], v[218:221], v[100:103]
	v_mfma_f32_16x16x32_bf16 v[96:99], v[156:159], v[214:217], v[96:99]
	v_mfma_f32_16x16x32_bf16 v[96:99], v[160:163], v[218:221], v[96:99]
	v_mfma_f32_16x16x32_bf16 v[60:63], v[174:177], v[190:193], v[60:63]
	v_mfma_f32_16x16x32_bf16 v[60:63], v[178:181], v[194:197], v[60:63]
	v_mfma_f32_16x16x32_bf16 v[56:59], v[182:185], v[190:193], v[56:59]
	v_mfma_f32_16x16x32_bf16 v[56:59], v[186:189], v[194:197], v[56:59]
	v_mfma_f32_16x16x32_bf16 v[52:55], v[174:177], v[198:201], v[52:55]
	v_mfma_f32_16x16x32_bf16 v[52:55], v[178:181], v[202:205], v[52:55]
	v_mfma_f32_16x16x32_bf16 v[48:51], v[182:185], v[198:201], v[48:51]
	v_mfma_f32_16x16x32_bf16 v[48:51], v[186:189], v[202:205], v[48:51]
	v_mfma_f32_16x16x32_bf16 v[44:47], v[174:177], v[206:209], v[44:47]
	v_mfma_f32_16x16x32_bf16 v[44:47], v[178:181], v[210:213], v[44:47]
	v_mfma_f32_16x16x32_bf16 v[40:43], v[182:185], v[206:209], v[40:43]
	v_mfma_f32_16x16x32_bf16 v[40:43], v[186:189], v[210:213], v[40:43]
	v_mfma_f32_16x16x32_bf16 v[36:39], v[174:177], v[214:217], v[36:39]
	v_mfma_f32_16x16x32_bf16 v[36:39], v[178:181], v[218:221], v[36:39]
	v_mfma_f32_16x16x32_bf16 v[32:35], v[182:185], v[214:217], v[32:35]
	v_mfma_f32_16x16x32_bf16 v[32:35], v[186:189], v[218:221], v[32:35]
	s_barrier
	s_add_i32 s35, s55, s36
	v_lshl_add_u64 v[222:223], s[26:27], 0, v[130:131]
	s_mov_b32 m0, s35
	v_lshl_add_u64 v[224:225], s[26:27], 0, v[134:135]
	global_load_lds_dwordx4 v[222:223], off
	s_add_i32 m0, s35, 0x2000
	s_add_u32 s58, s26, 0x100000
	s_addc_u32 s59, s27, 0
	s_add_i32 s35, s56, s36
	global_load_lds_dwordx4 v[224:225], off
	v_lshl_add_u64 v[190:191], s[58:59], 0, v[130:131]
	s_mov_b32 m0, s35
	v_lshl_add_u64 v[226:227], s[28:29], 0, v[128:129]
	global_load_lds_dwordx4 v[190:191], off
	v_lshl_add_u64 v[190:191], s[58:59], 0, v[134:135]
	s_add_i32 m0, s35, 0x2000
	v_lshl_add_u64 v[228:229], s[28:29], 0, v[132:133]
	global_load_lds_dwordx4 v[190:191], off
	s_mov_b32 m0, s41
	s_nop 0
	global_load_lds_dwordx4 v[226:227], off
	s_mov_b32 m0, s42
	s_nop 0
	global_load_lds_dwordx4 v[228:229], off
	ds_read_b128 v[190:193], v171 offset:16384
	ds_read_b128 v[194:197], v171 offset:17408
	ds_read_b128 v[198:201], v171 offset:18432
	ds_read_b128 v[202:205], v171 offset:19456
	ds_read_b128 v[206:209], v171 offset:20480
	ds_read_b128 v[210:213], v171 offset:21504
	ds_read_b128 v[214:217], v171 offset:22528
	ds_read_b128 v[218:221], v171 offset:23552
	s_waitcnt vmcnt(8)
	s_waitcnt lgkmcnt(0)
	s_barrier
	s_waitcnt lgkmcnt(0)
	v_mfma_f32_16x16x32_bf16 v[92:95], v[148:151], v[190:193], v[92:95]
	v_mfma_f32_16x16x32_bf16 v[92:95], v[152:155], v[194:197], v[92:95]
	v_mfma_f32_16x16x32_bf16 v[88:91], v[156:159], v[190:193], v[88:91]
	v_mfma_f32_16x16x32_bf16 v[88:91], v[160:163], v[194:197], v[88:91]
	v_mfma_f32_16x16x32_bf16 v[84:87], v[148:151], v[198:201], v[84:87]
	v_mfma_f32_16x16x32_bf16 v[84:87], v[152:155], v[202:205], v[84:87]
	v_mfma_f32_16x16x32_bf16 v[80:83], v[156:159], v[198:201], v[80:83]
	v_mfma_f32_16x16x32_bf16 v[80:83], v[160:163], v[202:205], v[80:83]
	v_mfma_f32_16x16x32_bf16 v[76:79], v[148:151], v[206:209], v[76:79]
	v_mfma_f32_16x16x32_bf16 v[76:79], v[152:155], v[210:213], v[76:79]
	v_mfma_f32_16x16x32_bf16 v[72:75], v[156:159], v[206:209], v[72:75]
	v_mfma_f32_16x16x32_bf16 v[72:75], v[160:163], v[210:213], v[72:75]
	v_mfma_f32_16x16x32_bf16 v[68:71], v[148:151], v[214:217], v[68:71]
	v_mfma_f32_16x16x32_bf16 v[68:71], v[152:155], v[218:221], v[68:71]
	v_mfma_f32_16x16x32_bf16 v[64:67], v[156:159], v[214:217], v[64:67]
	v_mfma_f32_16x16x32_bf16 v[64:67], v[160:163], v[218:221], v[64:67]
	v_mfma_f32_16x16x32_bf16 v[28:31], v[174:177], v[190:193], v[28:31]
	v_mfma_f32_16x16x32_bf16 v[28:31], v[178:181], v[194:197], v[28:31]
	v_mfma_f32_16x16x32_bf16 v[24:27], v[182:185], v[190:193], v[24:27]
	v_mfma_f32_16x16x32_bf16 v[24:27], v[186:189], v[194:197], v[24:27]
	v_mfma_f32_16x16x32_bf16 v[20:23], v[174:177], v[198:201], v[20:23]
	v_mfma_f32_16x16x32_bf16 v[20:23], v[178:181], v[202:205], v[20:23]
	v_mfma_f32_16x16x32_bf16 v[16:19], v[182:185], v[198:201], v[16:19]
	v_mfma_f32_16x16x32_bf16 v[16:19], v[186:189], v[202:205], v[16:19]
	v_mfma_f32_16x16x32_bf16 v[12:15], v[174:177], v[206:209], v[12:15]
	v_mfma_f32_16x16x32_bf16 v[12:15], v[178:181], v[210:213], v[12:15]
	v_mfma_f32_16x16x32_bf16 v[8:11], v[182:185], v[206:209], v[8:11]
	v_mfma_f32_16x16x32_bf16 v[8:11], v[186:189], v[210:213], v[8:11]
	v_mfma_f32_16x16x32_bf16 v[4:7], v[174:177], v[214:217], v[4:7]
	v_mfma_f32_16x16x32_bf16 v[4:7], v[178:181], v[218:221], v[4:7]
	v_mfma_f32_16x16x32_bf16 v[0:3], v[182:185], v[214:217], v[0:3]
	v_mfma_f32_16x16x32_bf16 v[0:3], v[186:189], v[218:221], v[0:3]
	s_barrier
	s_add_i32 s35, 0, 0x18000
	v_add_u32_e32 v136, s35, v165
	s_add_i32 s57, 0, 0x1c000
	ds_read_b128 v[148:151], v136
	ds_read_b128 v[152:155], v136 offset:1024
	ds_read_b128 v[156:159], v136 offset:2048
	ds_read_b128 v[160:163], v136 offset:3072
	v_add_u32_e32 v136, s57, v165
	ds_read_b128 v[174:177], v136
	ds_read_b128 v[178:181], v136 offset:1024
	ds_read_b128 v[182:185], v136 offset:2048
	ds_read_b128 v[186:189], v136 offset:3072
	s_add_u32 s28, s28, 0x100000
	s_addc_u32 s29, s29, 0
	s_mov_b32 m0, s43
	v_lshl_add_u64 v[190:191], s[28:29], 0, v[128:129]
	global_load_lds_dwordx4 v[190:191], off
	v_lshl_add_u64 v[190:191], s[28:29], 0, v[132:133]
	s_mov_b32 m0, s44
	s_nop 0
	global_load_lds_dwordx4 v[190:191], off
	ds_read_b128 v[190:193], v171 offset:32768
	ds_read_b128 v[194:197], v171 offset:33792
	ds_read_b128 v[198:201], v171 offset:34816
	ds_read_b128 v[202:205], v171 offset:35840
	ds_read_b128 v[206:209], v171 offset:36864
	ds_read_b128 v[210:213], v171 offset:37888
	ds_read_b128 v[214:217], v171 offset:38912
	ds_read_b128 v[218:221], v171 offset:39936
	s_waitcnt vmcnt(8)
	s_waitcnt lgkmcnt(0)
	s_barrier
	s_waitcnt lgkmcnt(0)
	v_mfma_f32_16x16x32_bf16 v[124:127], v[148:151], v[190:193], v[124:127]
	v_mfma_f32_16x16x32_bf16 v[124:127], v[152:155], v[194:197], v[124:127]
	v_mfma_f32_16x16x32_bf16 v[120:123], v[156:159], v[190:193], v[120:123]
	v_mfma_f32_16x16x32_bf16 v[120:123], v[160:163], v[194:197], v[120:123]
	v_mfma_f32_16x16x32_bf16 v[116:119], v[148:151], v[198:201], v[116:119]
	v_mfma_f32_16x16x32_bf16 v[116:119], v[152:155], v[202:205], v[116:119]
	v_mfma_f32_16x16x32_bf16 v[112:115], v[156:159], v[198:201], v[112:115]
	v_mfma_f32_16x16x32_bf16 v[112:115], v[160:163], v[202:205], v[112:115]
	v_mfma_f32_16x16x32_bf16 v[108:111], v[148:151], v[206:209], v[108:111]
	v_mfma_f32_16x16x32_bf16 v[108:111], v[152:155], v[210:213], v[108:111]
	v_mfma_f32_16x16x32_bf16 v[104:107], v[156:159], v[206:209], v[104:107]
	v_mfma_f32_16x16x32_bf16 v[104:107], v[160:163], v[210:213], v[104:107]
	v_mfma_f32_16x16x32_bf16 v[100:103], v[148:151], v[214:217], v[100:103]
	v_mfma_f32_16x16x32_bf16 v[100:103], v[152:155], v[218:221], v[100:103]
	v_mfma_f32_16x16x32_bf16 v[96:99], v[156:159], v[214:217], v[96:99]
	v_mfma_f32_16x16x32_bf16 v[96:99], v[160:163], v[218:221], v[96:99]
	v_mfma_f32_16x16x32_bf16 v[60:63], v[174:177], v[190:193], v[60:63]
	v_mfma_f32_16x16x32_bf16 v[60:63], v[178:181], v[194:197], v[60:63]
	v_mfma_f32_16x16x32_bf16 v[56:59], v[182:185], v[190:193], v[56:59]
	v_mfma_f32_16x16x32_bf16 v[56:59], v[186:189], v[194:197], v[56:59]
	v_mfma_f32_16x16x32_bf16 v[52:55], v[174:177], v[198:201], v[52:55]
	v_mfma_f32_16x16x32_bf16 v[52:55], v[178:181], v[202:205], v[52:55]
	v_mfma_f32_16x16x32_bf16 v[48:51], v[182:185], v[198:201], v[48:51]
	v_mfma_f32_16x16x32_bf16 v[48:51], v[186:189], v[202:205], v[48:51]
	v_mfma_f32_16x16x32_bf16 v[44:47], v[174:177], v[206:209], v[44:47]
	v_mfma_f32_16x16x32_bf16 v[44:47], v[178:181], v[210:213], v[44:47]
	v_mfma_f32_16x16x32_bf16 v[40:43], v[182:185], v[206:209], v[40:43]
	v_mfma_f32_16x16x32_bf16 v[40:43], v[186:189], v[210:213], v[40:43]
	v_mfma_f32_16x16x32_bf16 v[36:39], v[174:177], v[214:217], v[36:39]
	v_mfma_f32_16x16x32_bf16 v[36:39], v[178:181], v[218:221], v[36:39]
	v_mfma_f32_16x16x32_bf16 v[32:35], v[182:185], v[214:217], v[32:35]
	v_mfma_f32_16x16x32_bf16 v[32:35], v[186:189], v[218:221], v[32:35]
	s_barrier
	s_add_i32 s28, s35, s36
	v_lshl_add_u64 v[190:191], v[222:223], 0, s[12:13]
	s_mov_b32 m0, s28
	s_nop 0
	global_load_lds_dwordx4 v[190:191], off
	s_add_i32 m0, s28, 0x2000
	s_add_u32 s26, s26, 0x100800
	v_lshl_add_u64 v[190:191], v[224:225], 0, s[12:13]
	s_addc_u32 s27, s27, 0
	s_add_i32 s28, s57, s36
	global_load_lds_dwordx4 v[190:191], off
	v_lshl_add_u64 v[190:191], s[26:27], 0, v[130:131]
	s_mov_b32 m0, s28
	s_nop 0
	global_load_lds_dwordx4 v[190:191], off
	v_lshl_add_u64 v[190:191], s[26:27], 0, v[134:135]
	s_add_i32 m0, s28, 0x2000
	s_nop 0
	global_load_lds_dwordx4 v[190:191], off
	v_lshl_add_u64 v[190:191], v[226:227], 0, s[12:13]
	s_mov_b32 m0, s49
	s_nop 0
	global_load_lds_dwordx4 v[190:191], off
	v_lshl_add_u64 v[190:191], v[228:229], 0, s[12:13]
	s_mov_b32 m0, s50
	s_nop 0
	global_load_lds_dwordx4 v[190:191], off
	ds_read_b128 v[190:193], v171 offset:49152
	ds_read_b128 v[194:197], v171 offset:50176
	ds_read_b128 v[198:201], v171 offset:51200
	ds_read_b128 v[202:205], v171 offset:52224
	ds_read_b128 v[206:209], v171 offset:53248
	ds_read_b128 v[210:213], v171 offset:54272
	ds_read_b128 v[214:217], v171 offset:55296
	ds_read_b128 v[218:221], v171 offset:56320
	s_waitcnt vmcnt(8)
	s_waitcnt lgkmcnt(0)
	s_barrier
	s_waitcnt lgkmcnt(0)
	v_mfma_f32_16x16x32_bf16 v[92:95], v[148:151], v[190:193], v[92:95]
	v_mfma_f32_16x16x32_bf16 v[92:95], v[152:155], v[194:197], v[92:95]
	v_mfma_f32_16x16x32_bf16 v[88:91], v[156:159], v[190:193], v[88:91]
	v_mfma_f32_16x16x32_bf16 v[88:91], v[160:163], v[194:197], v[88:91]
	v_mfma_f32_16x16x32_bf16 v[84:87], v[148:151], v[198:201], v[84:87]
	v_mfma_f32_16x16x32_bf16 v[84:87], v[152:155], v[202:205], v[84:87]
	v_mfma_f32_16x16x32_bf16 v[80:83], v[156:159], v[198:201], v[80:83]
	v_mfma_f32_16x16x32_bf16 v[80:83], v[160:163], v[202:205], v[80:83]
	v_mfma_f32_16x16x32_bf16 v[76:79], v[148:151], v[206:209], v[76:79]
	v_mfma_f32_16x16x32_bf16 v[76:79], v[152:155], v[210:213], v[76:79]
	v_mfma_f32_16x16x32_bf16 v[72:75], v[156:159], v[206:209], v[72:75]
	v_mfma_f32_16x16x32_bf16 v[72:75], v[160:163], v[210:213], v[72:75]
	v_mfma_f32_16x16x32_bf16 v[68:71], v[148:151], v[214:217], v[68:71]
	v_mfma_f32_16x16x32_bf16 v[68:71], v[152:155], v[218:221], v[68:71]
	v_mfma_f32_16x16x32_bf16 v[64:67], v[156:159], v[214:217], v[64:67]
	v_mfma_f32_16x16x32_bf16 v[64:67], v[160:163], v[218:221], v[64:67]
	v_mfma_f32_16x16x32_bf16 v[28:31], v[174:177], v[190:193], v[28:31]
	v_mfma_f32_16x16x32_bf16 v[28:31], v[178:181], v[194:197], v[28:31]
	v_mfma_f32_16x16x32_bf16 v[24:27], v[182:185], v[190:193], v[24:27]
	v_mfma_f32_16x16x32_bf16 v[24:27], v[186:189], v[194:197], v[24:27]
	v_mfma_f32_16x16x32_bf16 v[20:23], v[174:177], v[198:201], v[20:23]
	v_mfma_f32_16x16x32_bf16 v[20:23], v[178:181], v[202:205], v[20:23]
	v_mfma_f32_16x16x32_bf16 v[16:19], v[182:185], v[198:201], v[16:19]
	v_mfma_f32_16x16x32_bf16 v[16:19], v[186:189], v[202:205], v[16:19]
	v_mfma_f32_16x16x32_bf16 v[12:15], v[174:177], v[206:209], v[12:15]
	v_mfma_f32_16x16x32_bf16 v[12:15], v[178:181], v[210:213], v[12:15]
	v_mfma_f32_16x16x32_bf16 v[8:11], v[182:185], v[206:209], v[8:11]
	v_mfma_f32_16x16x32_bf16 v[8:11], v[186:189], v[210:213], v[8:11]
	v_mfma_f32_16x16x32_bf16 v[4:7], v[174:177], v[214:217], v[4:7]
	v_mfma_f32_16x16x32_bf16 v[4:7], v[178:181], v[218:221], v[4:7]
	v_mfma_f32_16x16x32_bf16 v[0:3], v[182:185], v[214:217], v[0:3]
	v_mfma_f32_16x16x32_bf16 v[0:3], v[186:189], v[218:221], v[0:3]
	s_barrier
	s_add_i32 s34, s34, 2
	s_add_u32 s6, s6, 0x1000
	s_addc_u32 s7, s7, 0
	s_add_u32 s30, s30, 0x1000
	s_addc_u32 s31, s31, 0
	s_cmp_gt_u32 s34, 61
	s_cbranch_scc0 .LBB0_200
	s_and_b64 vcc, exec, s[0:1]
	s_cbranch_vccz .LBB0_203
	s_barrier

.LBB0_333:
	ds_read_b128 v[144:147], v152
	ds_read_b128 v[156:159], v152 offset:1024
	ds_read_b128 v[160:163], v152 offset:2048
	ds_read_b128 v[164:167], v152 offset:3072
	ds_read_b128 v[168:171], v153
	ds_read_b128 v[172:175], v153 offset:1024
	ds_read_b128 v[176:179], v153 offset:2048
	ds_read_b128 v[180:183], v153 offset:3072
	s_add_u32 s28, s24, 0x100
	s_addc_u32 s29, s25, 0
	s_cmp_eq_u32 s56, 60
	s_cselect_b32 s35, s13, s29
	s_cselect_b32 s34, s52, s28
	s_cselect_b32 s31, s11, s55
	s_cselect_b32 s30, s53, s54
	v_lshl_add_u64 v[184:185], s[24:25], 0, v[136:137]
	s_add_i32 m0, s21, 0xc000
	s_nop 0
	global_load_lds_dwordx4 v[184:185], off
	v_lshl_add_u64 v[184:185], s[24:25], 0, v[138:139]
	s_add_i32 m0, s21, 0xe000
	s_nop 0
	global_load_lds_dwordx4 v[184:185], off
	ds_read_b128 v[184:187], v154
	ds_read_b128 v[188:191], v154 offset:1024
	ds_read_b128 v[192:195], v154 offset:2048
	ds_read_b128 v[196:199], v154 offset:3072
	ds_read_b128 v[200:203], v154 offset:4096
	ds_read_b128 v[204:207], v154 offset:5120
	ds_read_b128 v[208:211], v154 offset:6144
	ds_read_b128 v[212:215], v154 offset:7168
	s_waitcnt vmcnt(8)
	s_waitcnt lgkmcnt(0)
	s_barrier
	s_waitcnt lgkmcnt(0)
	v_mfma_f32_16x16x32_bf16 v[124:127], v[144:147], v[184:187], v[124:127]
	v_mfma_f32_16x16x32_bf16 v[124:127], v[156:159], v[188:191], v[124:127]
	v_mfma_f32_16x16x32_bf16 v[120:123], v[160:163], v[184:187], v[120:123]
	v_mfma_f32_16x16x32_bf16 v[120:123], v[164:167], v[188:191], v[120:123]
	v_mfma_f32_16x16x32_bf16 v[116:119], v[144:147], v[192:195], v[116:119]
	v_mfma_f32_16x16x32_bf16 v[116:119], v[156:159], v[196:199], v[116:119]
	v_mfma_f32_16x16x32_bf16 v[108:111], v[160:163], v[192:195], v[108:111]
	v_mfma_f32_16x16x32_bf16 v[108:111], v[164:167], v[196:199], v[108:111]
	v_mfma_f32_16x16x32_bf16 v[100:103], v[144:147], v[200:203], v[100:103]
	v_mfma_f32_16x16x32_bf16 v[100:103], v[156:159], v[204:207], v[100:103]
	v_mfma_f32_16x16x32_bf16 v[92:95], v[160:163], v[200:203], v[92:95]
	v_mfma_f32_16x16x32_bf16 v[92:95], v[164:167], v[204:207], v[92:95]
	v_mfma_f32_16x16x32_bf16 v[84:87], v[144:147], v[208:211], v[84:87]
	v_mfma_f32_16x16x32_bf16 v[84:87], v[156:159], v[212:215], v[84:87]
	v_mfma_f32_16x16x32_bf16 v[76:79], v[160:163], v[208:211], v[76:79]
	v_mfma_f32_16x16x32_bf16 v[76:79], v[164:167], v[212:215], v[76:79]
	v_mfma_f32_16x16x32_bf16 v[112:115], v[168:171], v[184:187], v[112:115]
	v_mfma_f32_16x16x32_bf16 v[112:115], v[172:175], v[188:191], v[112:115]
	v_mfma_f32_16x16x32_bf16 v[104:107], v[176:179], v[184:187], v[104:107]
	v_mfma_f32_16x16x32_bf16 v[104:107], v[180:183], v[188:191], v[104:107]
	v_mfma_f32_16x16x32_bf16 v[96:99], v[168:171], v[192:195], v[96:99]
	v_mfma_f32_16x16x32_bf16 v[96:99], v[172:175], v[196:199], v[96:99]
	v_mfma_f32_16x16x32_bf16 v[88:91], v[176:179], v[192:195], v[88:91]
	v_mfma_f32_16x16x32_bf16 v[88:91], v[180:183], v[196:199], v[88:91]
	v_mfma_f32_16x16x32_bf16 v[80:83], v[168:171], v[200:203], v[80:83]
	v_mfma_f32_16x16x32_bf16 v[80:83], v[172:175], v[204:207], v[80:83]
	v_mfma_f32_16x16x32_bf16 v[72:75], v[176:179], v[200:203], v[72:75]
	v_mfma_f32_16x16x32_bf16 v[72:75], v[180:183], v[204:207], v[72:75]
	v_mfma_f32_16x16x32_bf16 v[68:71], v[168:171], v[208:211], v[68:71]
	v_mfma_f32_16x16x32_bf16 v[68:71], v[172:175], v[212:215], v[68:71]
	v_mfma_f32_16x16x32_bf16 v[64:67], v[176:179], v[208:211], v[64:67]
	v_mfma_f32_16x16x32_bf16 v[64:67], v[180:183], v[212:215], v[64:67]
	s_barrier
	s_add_i32 s24, s49, s41
	v_lshl_add_u64 v[216:217], s[30:31], 0, v[130:131]
	s_mov_b32 m0, s24
	v_lshl_add_u64 v[218:219], s[30:31], 0, v[134:135]
	global_load_lds_dwordx4 v[216:217], off
	s_add_i32 m0, s24, 0x2000
	s_add_u32 s24, s30, 0x100000
	s_addc_u32 s25, s31, 0
	s_add_i32 s57, s50, s41
	global_load_lds_dwordx4 v[218:219], off
	v_lshl_add_u64 v[184:185], s[24:25], 0, v[130:131]
	s_mov_b32 m0, s57
	v_lshl_add_u64 v[220:221], s[34:35], 0, v[128:129]
	global_load_lds_dwordx4 v[184:185], off
	v_lshl_add_u64 v[184:185], s[24:25], 0, v[134:135]
	s_add_i32 m0, s57, 0x2000
	v_lshl_add_u64 v[222:223], s[34:35], 0, v[132:133]
	global_load_lds_dwordx4 v[184:185], off
	s_mov_b32 m0, s21
	s_nop 0
	global_load_lds_dwordx4 v[220:221], off
	s_mov_b32 m0, s42
	s_nop 0
	global_load_lds_dwordx4 v[222:223], off
	ds_read_b128 v[184:187], v154 offset:16384
	ds_read_b128 v[188:191], v154 offset:17408
	ds_read_b128 v[192:195], v154 offset:18432
	ds_read_b128 v[196:199], v154 offset:19456
	ds_read_b128 v[200:203], v154 offset:20480
	ds_read_b128 v[204:207], v154 offset:21504
	ds_read_b128 v[208:211], v154 offset:22528
	ds_read_b128 v[212:215], v154 offset:23552
	s_waitcnt vmcnt(8)
	s_waitcnt lgkmcnt(0)
	s_barrier
	s_waitcnt lgkmcnt(0)
	v_mfma_f32_16x16x32_bf16 v[60:63], v[144:147], v[184:187], v[60:63]
	v_mfma_f32_16x16x32_bf16 v[60:63], v[156:159], v[188:191], v[60:63]
	v_mfma_f32_16x16x32_bf16 v[56:59], v[160:163], v[184:187], v[56:59]
	v_mfma_f32_16x16x32_bf16 v[56:59], v[164:167], v[188:191], v[56:59]
	v_mfma_f32_16x16x32_bf16 v[52:55], v[144:147], v[192:195], v[52:55]
	v_mfma_f32_16x16x32_bf16 v[52:55], v[156:159], v[196:199], v[52:55]
	v_mfma_f32_16x16x32_bf16 v[44:47], v[160:163], v[192:195], v[44:47]
	v_mfma_f32_16x16x32_bf16 v[44:47], v[164:167], v[196:199], v[44:47]
	v_mfma_f32_16x16x32_bf16 v[36:39], v[144:147], v[200:203], v[36:39]
	v_mfma_f32_16x16x32_bf16 v[36:39], v[156:159], v[204:207], v[36:39]
	v_mfma_f32_16x16x32_bf16 v[28:31], v[160:163], v[200:203], v[28:31]
	v_mfma_f32_16x16x32_bf16 v[28:31], v[164:167], v[204:207], v[28:31]
	v_mfma_f32_16x16x32_bf16 v[20:23], v[144:147], v[208:211], v[20:23]
	v_mfma_f32_16x16x32_bf16 v[20:23], v[156:159], v[212:215], v[20:23]
	v_mfma_f32_16x16x32_bf16 v[12:15], v[160:163], v[208:211], v[12:15]
	v_mfma_f32_16x16x32_bf16 v[12:15], v[164:167], v[212:215], v[12:15]
	v_mfma_f32_16x16x32_bf16 v[48:51], v[168:171], v[184:187], v[48:51]
	v_mfma_f32_16x16x32_bf16 v[48:51], v[172:175], v[188:191], v[48:51]
	v_mfma_f32_16x16x32_bf16 v[40:43], v[176:179], v[184:187], v[40:43]
	v_mfma_f32_16x16x32_bf16 v[40:43], v[180:183], v[188:191], v[40:43]
	v_mfma_f32_16x16x32_bf16 v[32:35], v[168:171], v[192:195], v[32:35]
	v_mfma_f32_16x16x32_bf16 v[32:35], v[172:175], v[196:199], v[32:35]
	v_mfma_f32_16x16x32_bf16 v[24:27], v[176:179], v[192:195], v[24:27]
	v_mfma_f32_16x16x32_bf16 v[24:27], v[180:183], v[196:199], v[24:27]
	v_mfma_f32_16x16x32_bf16 v[16:19], v[168:171], v[200:203], v[16:19]
	v_mfma_f32_16x16x32_bf16 v[16:19], v[172:175], v[204:207], v[16:19]
	v_mfma_f32_16x16x32_bf16 v[8:11], v[176:179], v[200:203], v[8:11]
	v_mfma_f32_16x16x32_bf16 v[8:11], v[180:183], v[204:207], v[8:11]
	v_mfma_f32_16x16x32_bf16 v[4:7], v[168:171], v[208:211], v[4:7]
	v_mfma_f32_16x16x32_bf16 v[4:7], v[172:175], v[212:215], v[4:7]
	v_mfma_f32_16x16x32_bf16 v[0:3], v[176:179], v[208:211], v[0:3]
	v_mfma_f32_16x16x32_bf16 v[0:3], v[180:183], v[212:215], v[0:3]
	s_barrier
	s_add_i32 s57, 0, 0x18000
	v_add_u32_e32 v155, s57, v149
	s_add_i32 s58, 0, 0x1c000
	ds_read_b128 v[144:147], v155
	ds_read_b128 v[156:159], v155 offset:1024
	ds_read_b128 v[160:163], v155 offset:2048
	ds_read_b128 v[164:167], v155 offset:3072
	v_add_u32_e32 v155, s58, v149
	ds_read_b128 v[168:171], v155
	ds_read_b128 v[172:175], v155 offset:1024
	ds_read_b128 v[176:179], v155 offset:2048
	ds_read_b128 v[180:183], v155 offset:3072
	s_add_u32 s24, s34, 0x100000
	s_addc_u32 s25, s35, 0
	s_mov_b32 m0, s43
	v_lshl_add_u64 v[184:185], s[24:25], 0, v[128:129]
	global_load_lds_dwordx4 v[184:185], off
	v_lshl_add_u64 v[184:185], s[24:25], 0, v[132:133]
	s_mov_b32 m0, s44
	s_nop 0
	global_load_lds_dwordx4 v[184:185], off
	ds_read_b128 v[184:187], v154 offset:32768
	ds_read_b128 v[188:191], v154 offset:33792
	ds_read_b128 v[192:195], v154 offset:34816
	ds_read_b128 v[196:199], v154 offset:35840
	ds_read_b128 v[200:203], v154 offset:36864
	ds_read_b128 v[204:207], v154 offset:37888
	ds_read_b128 v[208:211], v154 offset:38912
	ds_read_b128 v[212:215], v154 offset:39936
	s_waitcnt vmcnt(8)
	s_waitcnt lgkmcnt(0)
	s_barrier
	s_waitcnt lgkmcnt(0)
	v_mfma_f32_16x16x32_bf16 v[124:127], v[144:147], v[184:187], v[124:127]
	v_mfma_f32_16x16x32_bf16 v[124:127], v[156:159], v[188:191], v[124:127]
	v_mfma_f32_16x16x32_bf16 v[120:123], v[160:163], v[184:187], v[120:123]
	v_mfma_f32_16x16x32_bf16 v[120:123], v[164:167], v[188:191], v[120:123]
	v_mfma_f32_16x16x32_bf16 v[116:119], v[144:147], v[192:195], v[116:119]
	v_mfma_f32_16x16x32_bf16 v[116:119], v[156:159], v[196:199], v[116:119]
	v_mfma_f32_16x16x32_bf16 v[108:111], v[160:163], v[192:195], v[108:111]
	v_mfma_f32_16x16x32_bf16 v[108:111], v[164:167], v[196:199], v[108:111]
	v_mfma_f32_16x16x32_bf16 v[100:103], v[144:147], v[200:203], v[100:103]
	v_mfma_f32_16x16x32_bf16 v[100:103], v[156:159], v[204:207], v[100:103]
	v_mfma_f32_16x16x32_bf16 v[92:95], v[160:163], v[200:203], v[92:95]
	v_mfma_f32_16x16x32_bf16 v[92:95], v[164:167], v[204:207], v[92:95]
	v_mfma_f32_16x16x32_bf16 v[84:87], v[144:147], v[208:211], v[84:87]
	v_mfma_f32_16x16x32_bf16 v[84:87], v[156:159], v[212:215], v[84:87]
	v_mfma_f32_16x16x32_bf16 v[76:79], v[160:163], v[208:211], v[76:79]
	v_mfma_f32_16x16x32_bf16 v[76:79], v[164:167], v[212:215], v[76:79]
	v_mfma_f32_16x16x32_bf16 v[112:115], v[168:171], v[184:187], v[112:115]
	v_mfma_f32_16x16x32_bf16 v[112:115], v[172:175], v[188:191], v[112:115]
	v_mfma_f32_16x16x32_bf16 v[104:107], v[176:179], v[184:187], v[104:107]
	v_mfma_f32_16x16x32_bf16 v[104:107], v[180:183], v[188:191], v[104:107]
	v_mfma_f32_16x16x32_bf16 v[96:99], v[168:171], v[192:195], v[96:99]
	v_mfma_f32_16x16x32_bf16 v[96:99], v[172:175], v[196:199], v[96:99]
	v_mfma_f32_16x16x32_bf16 v[88:91], v[176:179], v[192:195], v[88:91]
	v_mfma_f32_16x16x32_bf16 v[88:91], v[180:183], v[196:199], v[88:91]
	v_mfma_f32_16x16x32_bf16 v[80:83], v[168:171], v[200:203], v[80:83]
	v_mfma_f32_16x16x32_bf16 v[80:83], v[172:175], v[204:207], v[80:83]
	v_mfma_f32_16x16x32_bf16 v[72:75], v[176:179], v[200:203], v[72:75]
	v_mfma_f32_16x16x32_bf16 v[72:75], v[180:183], v[204:207], v[72:75]
	v_mfma_f32_16x16x32_bf16 v[68:71], v[168:171], v[208:211], v[68:71]
	v_mfma_f32_16x16x32_bf16 v[68:71], v[172:175], v[212:215], v[68:71]
	v_mfma_f32_16x16x32_bf16 v[64:67], v[176:179], v[208:211], v[64:67]
	v_mfma_f32_16x16x32_bf16 v[64:67], v[180:183], v[212:215], v[64:67]
	s_barrier
	s_add_i32 s24, s57, s41
	v_lshl_add_u64 v[184:185], v[216:217], 0, s[8:9]
	s_mov_b32 m0, s24
	s_nop 0
	global_load_lds_dwordx4 v[184:185], off
	s_add_i32 m0, s24, 0x2000
	s_add_u32 s24, s30, 0x100080
	v_lshl_add_u64 v[184:185], v[218:219], 0, s[8:9]
	s_addc_u32 s25, s31, 0
	s_add_i32 s30, s58, s41
	global_load_lds_dwordx4 v[184:185], off
	v_lshl_add_u64 v[184:185], s[24:25], 0, v[130:131]
	s_mov_b32 m0, s30
	s_nop 0
	global_load_lds_dwordx4 v[184:185], off
	v_lshl_add_u64 v[184:185], s[24:25], 0, v[134:135]
	s_add_i32 m0, s30, 0x2000
	s_nop 0
	global_load_lds_dwordx4 v[184:185], off
	v_lshl_add_u64 v[184:185], v[220:221], 0, s[8:9]
	s_mov_b32 m0, s46
	s_nop 0
	global_load_lds_dwordx4 v[184:185], off
	v_lshl_add_u64 v[184:185], v[222:223], 0, s[8:9]
	s_mov_b32 m0, s47
	s_nop 0
	global_load_lds_dwordx4 v[184:185], off
	ds_read_b128 v[184:187], v154 offset:49152
	ds_read_b128 v[188:191], v154 offset:50176
	ds_read_b128 v[192:195], v154 offset:51200
	ds_read_b128 v[196:199], v154 offset:52224
	ds_read_b128 v[200:203], v154 offset:53248
	ds_read_b128 v[204:207], v154 offset:54272
	ds_read_b128 v[208:211], v154 offset:55296
	ds_read_b128 v[212:215], v154 offset:56320
	s_waitcnt vmcnt(8)
	s_waitcnt lgkmcnt(0)
	s_barrier
	s_waitcnt lgkmcnt(0)
	v_mfma_f32_16x16x32_bf16 v[60:63], v[144:147], v[184:187], v[60:63]
	v_mfma_f32_16x16x32_bf16 v[60:63], v[156:159], v[188:191], v[60:63]
	v_mfma_f32_16x16x32_bf16 v[56:59], v[160:163], v[184:187], v[56:59]
	v_mfma_f32_16x16x32_bf16 v[56:59], v[164:167], v[188:191], v[56:59]
	v_mfma_f32_16x16x32_bf16 v[52:55], v[144:147], v[192:195], v[52:55]
	v_mfma_f32_16x16x32_bf16 v[52:55], v[156:159], v[196:199], v[52:55]
	v_mfma_f32_16x16x32_bf16 v[44:47], v[160:163], v[192:195], v[44:47]
	v_mfma_f32_16x16x32_bf16 v[44:47], v[164:167], v[196:199], v[44:47]
	v_mfma_f32_16x16x32_bf16 v[36:39], v[144:147], v[200:203], v[36:39]
	v_mfma_f32_16x16x32_bf16 v[36:39], v[156:159], v[204:207], v[36:39]
	v_mfma_f32_16x16x32_bf16 v[28:31], v[160:163], v[200:203], v[28:31]
	v_mfma_f32_16x16x32_bf16 v[28:31], v[164:167], v[204:207], v[28:31]
	v_mfma_f32_16x16x32_bf16 v[20:23], v[144:147], v[208:211], v[20:23]
	v_mfma_f32_16x16x32_bf16 v[20:23], v[156:159], v[212:215], v[20:23]
	v_mfma_f32_16x16x32_bf16 v[12:15], v[160:163], v[208:211], v[12:15]
	v_mfma_f32_16x16x32_bf16 v[12:15], v[164:167], v[212:215], v[12:15]
	v_mfma_f32_16x16x32_bf16 v[48:51], v[168:171], v[184:187], v[48:51]
	v_mfma_f32_16x16x32_bf16 v[48:51], v[172:175], v[188:191], v[48:51]
	v_mfma_f32_16x16x32_bf16 v[40:43], v[176:179], v[184:187], v[40:43]
	v_mfma_f32_16x16x32_bf16 v[40:43], v[180:183], v[188:191], v[40:43]
	v_mfma_f32_16x16x32_bf16 v[32:35], v[168:171], v[192:195], v[32:35]
	v_mfma_f32_16x16x32_bf16 v[32:35], v[172:175], v[196:199], v[32:35]
	v_mfma_f32_16x16x32_bf16 v[24:27], v[176:179], v[192:195], v[24:27]
	v_mfma_f32_16x16x32_bf16 v[24:27], v[180:183], v[196:199], v[24:27]
	v_mfma_f32_16x16x32_bf16 v[16:19], v[168:171], v[200:203], v[16:19]
	v_mfma_f32_16x16x32_bf16 v[16:19], v[172:175], v[204:207], v[16:19]
	v_mfma_f32_16x16x32_bf16 v[8:11], v[176:179], v[200:203], v[8:11]
	v_mfma_f32_16x16x32_bf16 v[8:11], v[180:183], v[204:207], v[8:11]
	v_mfma_f32_16x16x32_bf16 v[4:7], v[168:171], v[208:211], v[4:7]
	v_mfma_f32_16x16x32_bf16 v[4:7], v[172:175], v[212:215], v[4:7]
	v_mfma_f32_16x16x32_bf16 v[0:3], v[176:179], v[208:211], v[0:3]
	v_mfma_f32_16x16x32_bf16 v[0:3], v[180:183], v[212:215], v[0:3]
	s_barrier
	s_add_i32 s56, s56, 2
	s_add_u32 s54, s54, 0x100
	s_addc_u32 s55, s55, 0
	s_cmp_gt_u32 s56, 61
	s_mov_b64 s[24:25], s[28:29]
	s_cbranch_scc0 .LBB0_333
	s_and_b64 vcc, exec, s[0:1]
	s_cbranch_vccz .LBB0_336
	s_barrier

.LBB0_1202:
	ds_read_b128 v[128:131], v176
	ds_read_b128 v[132:135], v176 offset:1024
	ds_read_b128 v[136:139], v176 offset:2048
	ds_read_b128 v[140:143], v176 offset:3072
	ds_read_b128 v[144:147], v177
	ds_read_b128 v[148:151], v177 offset:1024
	ds_read_b128 v[180:183], v177 offset:2048
	ds_read_b128 v[184:187], v177 offset:3072
	s_add_u32 s30, s28, 0xfff00080
	s_addc_u32 s31, s29, -1
	s_cmp_eq_u32 s40, 60
	s_cselect_b32 s35, s23, s31
	s_cselect_b32 s34, s36, s30
	s_cselect_b32 s31, s21, s39
	s_cselect_b32 s30, s37, s38
	v_lshl_add_u64 v[172:173], s[28:29], 0, v[164:165]
	s_add_i32 m0, s7, 0xc000
	s_nop 0
	global_load_lds_dwordx4 v[172:173], off
	v_lshl_add_u64 v[172:173], s[28:29], 0, v[166:167]
	s_add_i32 m0, s7, 0xe000
	s_nop 0
	global_load_lds_dwordx4 v[172:173], off
	ds_read_b128 v[188:191], v178
	ds_read_b128 v[192:195], v178 offset:1024
	ds_read_b128 v[196:199], v178 offset:2048
	ds_read_b128 v[200:203], v178 offset:3072
	ds_read_b128 v[204:207], v178 offset:4096
	ds_read_b128 v[208:211], v178 offset:5120
	ds_read_b128 v[212:215], v178 offset:6144
	ds_read_b128 v[216:219], v178 offset:7168
	s_waitcnt vmcnt(8)
	s_waitcnt lgkmcnt(0)
	s_barrier
	s_waitcnt lgkmcnt(0)
	v_mfma_f32_16x16x32_bf16 v[124:127], v[128:131], v[188:191], v[124:127]
	v_mfma_f32_16x16x32_bf16 v[124:127], v[132:135], v[192:195], v[124:127]
	v_mfma_f32_16x16x32_bf16 v[120:123], v[136:139], v[188:191], v[120:123]
	v_mfma_f32_16x16x32_bf16 v[120:123], v[140:143], v[192:195], v[120:123]
	v_mfma_f32_16x16x32_bf16 v[108:111], v[128:131], v[196:199], v[108:111]
	v_mfma_f32_16x16x32_bf16 v[108:111], v[132:135], v[200:203], v[108:111]
	v_mfma_f32_16x16x32_bf16 v[104:107], v[136:139], v[196:199], v[104:107]
	v_mfma_f32_16x16x32_bf16 v[104:107], v[140:143], v[200:203], v[104:107]
	v_mfma_f32_16x16x32_bf16 v[92:95], v[128:131], v[204:207], v[92:95]
	v_mfma_f32_16x16x32_bf16 v[92:95], v[132:135], v[208:211], v[92:95]
	v_mfma_f32_16x16x32_bf16 v[88:91], v[136:139], v[204:207], v[88:91]
	v_mfma_f32_16x16x32_bf16 v[88:91], v[140:143], v[208:211], v[88:91]
	v_mfma_f32_16x16x32_bf16 v[76:79], v[128:131], v[212:215], v[76:79]
	v_mfma_f32_16x16x32_bf16 v[76:79], v[132:135], v[216:219], v[76:79]
	v_mfma_f32_16x16x32_bf16 v[72:75], v[136:139], v[212:215], v[72:75]
	v_mfma_f32_16x16x32_bf16 v[72:75], v[140:143], v[216:219], v[72:75]
	v_mfma_f32_16x16x32_bf16 v[116:119], v[144:147], v[188:191], v[116:119]
	v_mfma_f32_16x16x32_bf16 v[116:119], v[148:151], v[192:195], v[116:119]
	v_mfma_f32_16x16x32_bf16 v[112:115], v[180:183], v[188:191], v[112:115]
	v_mfma_f32_16x16x32_bf16 v[112:115], v[184:187], v[192:195], v[112:115]
	v_mfma_f32_16x16x32_bf16 v[100:103], v[144:147], v[196:199], v[100:103]
	v_mfma_f32_16x16x32_bf16 v[100:103], v[148:151], v[200:203], v[100:103]
	v_mfma_f32_16x16x32_bf16 v[96:99], v[180:183], v[196:199], v[96:99]
	v_mfma_f32_16x16x32_bf16 v[96:99], v[184:187], v[200:203], v[96:99]
	v_mfma_f32_16x16x32_bf16 v[84:87], v[144:147], v[204:207], v[84:87]
	v_mfma_f32_16x16x32_bf16 v[84:87], v[148:151], v[208:211], v[84:87]
	v_mfma_f32_16x16x32_bf16 v[80:83], v[180:183], v[204:207], v[80:83]
	v_mfma_f32_16x16x32_bf16 v[80:83], v[184:187], v[208:211], v[80:83]
	v_mfma_f32_16x16x32_bf16 v[68:71], v[144:147], v[212:215], v[68:71]
	v_mfma_f32_16x16x32_bf16 v[68:71], v[148:151], v[216:219], v[68:71]
	v_mfma_f32_16x16x32_bf16 v[64:67], v[180:183], v[212:215], v[64:67]
	v_mfma_f32_16x16x32_bf16 v[64:67], v[184:187], v[216:219], v[64:67]
	s_barrier
	s_add_i32 s41, s68, s33
	v_lshl_add_u64 v[172:173], s[30:31], 0, v[154:155]
	s_mov_b32 m0, s41
	v_lshl_add_u64 v[220:221], s[30:31], 0, v[158:159]
	global_load_lds_dwordx4 v[172:173], off
	s_add_i32 m0, s41, 0x2000
	s_add_u32 s42, s30, 0x100000
	s_addc_u32 s43, s31, 0
	s_add_i32 s41, s69, s33
	global_load_lds_dwordx4 v[220:221], off
	v_lshl_add_u64 v[188:189], s[42:43], 0, v[154:155]
	s_mov_b32 m0, s41
	v_lshl_add_u64 v[222:223], s[34:35], 0, v[152:153]
	global_load_lds_dwordx4 v[188:189], off
	v_lshl_add_u64 v[188:189], s[42:43], 0, v[158:159]
	s_add_i32 m0, s41, 0x2000
	v_lshl_add_u64 v[224:225], s[34:35], 0, v[156:157]
	global_load_lds_dwordx4 v[188:189], off
	s_mov_b32 m0, s7
	s_nop 0
	global_load_lds_dwordx4 v[222:223], off
	s_mov_b32 m0, s59
	s_nop 0
	global_load_lds_dwordx4 v[224:225], off
	ds_read_b128 v[188:191], v178 offset:16384
	ds_read_b128 v[192:195], v178 offset:17408
	ds_read_b128 v[196:199], v178 offset:18432
	ds_read_b128 v[200:203], v178 offset:19456
	ds_read_b128 v[204:207], v178 offset:20480
	ds_read_b128 v[208:211], v178 offset:21504
	ds_read_b128 v[212:215], v178 offset:22528
	ds_read_b128 v[216:219], v178 offset:23552
	s_waitcnt vmcnt(8)
	s_waitcnt lgkmcnt(0)
	s_barrier
	s_waitcnt lgkmcnt(0)
	v_mfma_f32_16x16x32_bf16 v[60:63], v[128:131], v[188:191], v[60:63]
	v_mfma_f32_16x16x32_bf16 v[60:63], v[132:135], v[192:195], v[60:63]
	v_mfma_f32_16x16x32_bf16 v[56:59], v[136:139], v[188:191], v[56:59]
	v_mfma_f32_16x16x32_bf16 v[56:59], v[140:143], v[192:195], v[56:59]
	v_mfma_f32_16x16x32_bf16 v[44:47], v[128:131], v[196:199], v[44:47]
	v_mfma_f32_16x16x32_bf16 v[44:47], v[132:135], v[200:203], v[44:47]
	v_mfma_f32_16x16x32_bf16 v[40:43], v[136:139], v[196:199], v[40:43]
	v_mfma_f32_16x16x32_bf16 v[40:43], v[140:143], v[200:203], v[40:43]
	v_mfma_f32_16x16x32_bf16 v[28:31], v[128:131], v[204:207], v[28:31]
	v_mfma_f32_16x16x32_bf16 v[28:31], v[132:135], v[208:211], v[28:31]
	v_mfma_f32_16x16x32_bf16 v[24:27], v[136:139], v[204:207], v[24:27]
	v_mfma_f32_16x16x32_bf16 v[24:27], v[140:143], v[208:211], v[24:27]
	v_mfma_f32_16x16x32_bf16 v[12:15], v[128:131], v[212:215], v[12:15]
	v_mfma_f32_16x16x32_bf16 v[12:15], v[132:135], v[216:219], v[12:15]
	v_mfma_f32_16x16x32_bf16 v[8:11], v[136:139], v[212:215], v[8:11]
	v_mfma_f32_16x16x32_bf16 v[8:11], v[140:143], v[216:219], v[8:11]
	v_mfma_f32_16x16x32_bf16 v[52:55], v[144:147], v[188:191], v[52:55]
	v_mfma_f32_16x16x32_bf16 v[52:55], v[148:151], v[192:195], v[52:55]
	v_mfma_f32_16x16x32_bf16 v[48:51], v[180:183], v[188:191], v[48:51]
	v_mfma_f32_16x16x32_bf16 v[48:51], v[184:187], v[192:195], v[48:51]
	v_mfma_f32_16x16x32_bf16 v[36:39], v[144:147], v[196:199], v[36:39]
	v_mfma_f32_16x16x32_bf16 v[36:39], v[148:151], v[200:203], v[36:39]
	v_mfma_f32_16x16x32_bf16 v[32:35], v[180:183], v[196:199], v[32:35]
	v_mfma_f32_16x16x32_bf16 v[32:35], v[184:187], v[200:203], v[32:35]
	v_mfma_f32_16x16x32_bf16 v[20:23], v[144:147], v[204:207], v[20:23]
	v_mfma_f32_16x16x32_bf16 v[20:23], v[148:151], v[208:211], v[20:23]
	v_mfma_f32_16x16x32_bf16 v[16:19], v[180:183], v[204:207], v[16:19]
	v_mfma_f32_16x16x32_bf16 v[16:19], v[184:187], v[208:211], v[16:19]
	v_mfma_f32_16x16x32_bf16 v[4:7], v[144:147], v[212:215], v[4:7]
	v_mfma_f32_16x16x32_bf16 v[4:7], v[148:151], v[216:219], v[4:7]
	v_mfma_f32_16x16x32_bf16 v[0:3], v[180:183], v[212:215], v[0:3]
	v_mfma_f32_16x16x32_bf16 v[0:3], v[184:187], v[216:219], v[0:3]
	s_barrier
	s_add_i32 s41, 0, 0x18000
	s_add_i32 s42, 0, 0x1c000
	v_add_u32_e32 v140, s41, v174
	v_add_u32_e32 v184, s42, v174
	ds_read_b128 v[128:131], v140
	ds_read_b128 v[132:135], v140 offset:1024
	ds_read_b128 v[136:139], v140 offset:2048
	ds_read_b128 v[140:143], v140 offset:3072
	ds_read_b128 v[144:147], v184
	ds_read_b128 v[148:151], v184 offset:1024
	ds_read_b128 v[180:183], v184 offset:2048
	ds_read_b128 v[184:187], v184 offset:3072
	s_add_u32 s34, s34, 0x100000
	s_addc_u32 s35, s35, 0
	s_mov_b32 m0, s60
	v_lshl_add_u64 v[188:189], s[34:35], 0, v[152:153]
	global_load_lds_dwordx4 v[188:189], off
	v_lshl_add_u64 v[188:189], s[34:35], 0, v[156:157]
	s_mov_b32 m0, s61
	s_nop 0
	global_load_lds_dwordx4 v[188:189], off
	ds_read_b128 v[188:191], v178 offset:32768
	ds_read_b128 v[192:195], v178 offset:33792
	ds_read_b128 v[196:199], v178 offset:34816
	ds_read_b128 v[200:203], v178 offset:35840
	ds_read_b128 v[204:207], v178 offset:36864
	ds_read_b128 v[208:211], v178 offset:37888
	ds_read_b128 v[212:215], v178 offset:38912
	ds_read_b128 v[216:219], v178 offset:39936
	s_waitcnt vmcnt(8)
	s_waitcnt lgkmcnt(0)
	s_barrier
	s_waitcnt lgkmcnt(0)
	v_mfma_f32_16x16x32_bf16 v[124:127], v[128:131], v[188:191], v[124:127]
	v_mfma_f32_16x16x32_bf16 v[124:127], v[132:135], v[192:195], v[124:127]
	v_mfma_f32_16x16x32_bf16 v[120:123], v[136:139], v[188:191], v[120:123]
	v_mfma_f32_16x16x32_bf16 v[120:123], v[140:143], v[192:195], v[120:123]
	v_mfma_f32_16x16x32_bf16 v[108:111], v[128:131], v[196:199], v[108:111]
	v_mfma_f32_16x16x32_bf16 v[108:111], v[132:135], v[200:203], v[108:111]
	v_mfma_f32_16x16x32_bf16 v[104:107], v[136:139], v[196:199], v[104:107]
	v_mfma_f32_16x16x32_bf16 v[104:107], v[140:143], v[200:203], v[104:107]
	v_mfma_f32_16x16x32_bf16 v[92:95], v[128:131], v[204:207], v[92:95]
	v_mfma_f32_16x16x32_bf16 v[92:95], v[132:135], v[208:211], v[92:95]
	v_mfma_f32_16x16x32_bf16 v[88:91], v[136:139], v[204:207], v[88:91]
	v_mfma_f32_16x16x32_bf16 v[88:91], v[140:143], v[208:211], v[88:91]
	v_mfma_f32_16x16x32_bf16 v[76:79], v[128:131], v[212:215], v[76:79]
	v_mfma_f32_16x16x32_bf16 v[76:79], v[132:135], v[216:219], v[76:79]
	v_mfma_f32_16x16x32_bf16 v[72:75], v[136:139], v[212:215], v[72:75]
	v_mfma_f32_16x16x32_bf16 v[72:75], v[140:143], v[216:219], v[72:75]
	v_mfma_f32_16x16x32_bf16 v[116:119], v[144:147], v[188:191], v[116:119]
	v_mfma_f32_16x16x32_bf16 v[116:119], v[148:151], v[192:195], v[116:119]
	v_mfma_f32_16x16x32_bf16 v[112:115], v[180:183], v[188:191], v[112:115]
	v_mfma_f32_16x16x32_bf16 v[112:115], v[184:187], v[192:195], v[112:115]
	v_mfma_f32_16x16x32_bf16 v[100:103], v[144:147], v[196:199], v[100:103]
	v_mfma_f32_16x16x32_bf16 v[100:103], v[148:151], v[200:203], v[100:103]
	v_mfma_f32_16x16x32_bf16 v[96:99], v[180:183], v[196:199], v[96:99]
	v_mfma_f32_16x16x32_bf16 v[96:99], v[184:187], v[200:203], v[96:99]
	v_mfma_f32_16x16x32_bf16 v[84:87], v[144:147], v[204:207], v[84:87]
	v_mfma_f32_16x16x32_bf16 v[84:87], v[148:151], v[208:211], v[84:87]
	v_mfma_f32_16x16x32_bf16 v[80:83], v[180:183], v[204:207], v[80:83]
	v_mfma_f32_16x16x32_bf16 v[80:83], v[184:187], v[208:211], v[80:83]
	v_mfma_f32_16x16x32_bf16 v[68:71], v[144:147], v[212:215], v[68:71]
	v_mfma_f32_16x16x32_bf16 v[68:71], v[148:151], v[216:219], v[68:71]
	v_mfma_f32_16x16x32_bf16 v[64:67], v[180:183], v[212:215], v[64:67]
	v_mfma_f32_16x16x32_bf16 v[64:67], v[184:187], v[216:219], v[64:67]
	s_barrier
	s_add_i32 s34, s41, s33
	v_lshl_add_u64 v[172:173], v[172:173], 0, s[16:17]
	s_mov_b32 m0, s34
	s_nop 0
	global_load_lds_dwordx4 v[172:173], off
	s_add_i32 m0, s34, 0x2000
	s_add_u32 s30, s30, 0x100800
	v_lshl_add_u64 v[172:173], v[220:221], 0, s[16:17]
	s_addc_u32 s31, s31, 0
	s_add_i32 s34, s42, s33
	global_load_lds_dwordx4 v[172:173], off
	v_lshl_add_u64 v[172:173], s[30:31], 0, v[154:155]
	s_mov_b32 m0, s34
	s_nop 0
	global_load_lds_dwordx4 v[172:173], off
	v_lshl_add_u64 v[172:173], s[30:31], 0, v[158:159]
	s_add_i32 m0, s34, 0x2000
	s_nop 0
	global_load_lds_dwordx4 v[172:173], off
	v_lshl_add_u64 v[172:173], v[222:223], 0, s[18:19]
	s_mov_b32 m0, s63
	s_nop 0
	global_load_lds_dwordx4 v[172:173], off
	v_lshl_add_u64 v[172:173], v[224:225], 0, s[18:19]
	s_mov_b32 m0, s64
	s_nop 0
	global_load_lds_dwordx4 v[172:173], off
	ds_read_b128 v[188:191], v178 offset:49152
	ds_read_b128 v[192:195], v178 offset:50176
	ds_read_b128 v[196:199], v178 offset:51200
	ds_read_b128 v[200:203], v178 offset:52224
	ds_read_b128 v[204:207], v178 offset:53248
	ds_read_b128 v[208:211], v178 offset:54272
	ds_read_b128 v[212:215], v178 offset:55296
	ds_read_b128 v[216:219], v178 offset:56320
	s_waitcnt vmcnt(8)
	s_waitcnt lgkmcnt(0)
	s_barrier
	s_waitcnt lgkmcnt(0)
	v_mfma_f32_16x16x32_bf16 v[60:63], v[128:131], v[188:191], v[60:63]
	v_mfma_f32_16x16x32_bf16 v[60:63], v[132:135], v[192:195], v[60:63]
	v_mfma_f32_16x16x32_bf16 v[56:59], v[136:139], v[188:191], v[56:59]
	v_mfma_f32_16x16x32_bf16 v[56:59], v[140:143], v[192:195], v[56:59]
	v_mfma_f32_16x16x32_bf16 v[44:47], v[128:131], v[196:199], v[44:47]
	v_mfma_f32_16x16x32_bf16 v[44:47], v[132:135], v[200:203], v[44:47]
	v_mfma_f32_16x16x32_bf16 v[40:43], v[136:139], v[196:199], v[40:43]
	v_mfma_f32_16x16x32_bf16 v[40:43], v[140:143], v[200:203], v[40:43]
	v_mfma_f32_16x16x32_bf16 v[28:31], v[128:131], v[204:207], v[28:31]
	v_mfma_f32_16x16x32_bf16 v[28:31], v[132:135], v[208:211], v[28:31]
	v_mfma_f32_16x16x32_bf16 v[24:27], v[136:139], v[204:207], v[24:27]
	v_mfma_f32_16x16x32_bf16 v[24:27], v[140:143], v[208:211], v[24:27]
	v_mfma_f32_16x16x32_bf16 v[12:15], v[128:131], v[212:215], v[12:15]
	v_mfma_f32_16x16x32_bf16 v[12:15], v[132:135], v[216:219], v[12:15]
	v_mfma_f32_16x16x32_bf16 v[8:11], v[136:139], v[212:215], v[8:11]
	v_mfma_f32_16x16x32_bf16 v[8:11], v[140:143], v[216:219], v[8:11]
	v_mfma_f32_16x16x32_bf16 v[52:55], v[144:147], v[188:191], v[52:55]
	v_mfma_f32_16x16x32_bf16 v[52:55], v[148:151], v[192:195], v[52:55]
	v_mfma_f32_16x16x32_bf16 v[48:51], v[180:183], v[188:191], v[48:51]
	v_mfma_f32_16x16x32_bf16 v[48:51], v[184:187], v[192:195], v[48:51]
	v_mfma_f32_16x16x32_bf16 v[36:39], v[144:147], v[196:199], v[36:39]
	v_mfma_f32_16x16x32_bf16 v[36:39], v[148:151], v[200:203], v[36:39]
	v_mfma_f32_16x16x32_bf16 v[32:35], v[180:183], v[196:199], v[32:35]
	v_mfma_f32_16x16x32_bf16 v[32:35], v[184:187], v[200:203], v[32:35]
	v_mfma_f32_16x16x32_bf16 v[20:23], v[144:147], v[204:207], v[20:23]
	v_mfma_f32_16x16x32_bf16 v[20:23], v[148:151], v[208:211], v[20:23]
	v_mfma_f32_16x16x32_bf16 v[16:19], v[180:183], v[204:207], v[16:19]
	v_mfma_f32_16x16x32_bf16 v[16:19], v[184:187], v[208:211], v[16:19]
	v_mfma_f32_16x16x32_bf16 v[4:7], v[144:147], v[212:215], v[4:7]
	v_mfma_f32_16x16x32_bf16 v[4:7], v[148:151], v[216:219], v[4:7]
	v_mfma_f32_16x16x32_bf16 v[0:3], v[180:183], v[212:215], v[0:3]
	v_mfma_f32_16x16x32_bf16 v[0:3], v[184:187], v[216:219], v[0:3]
	s_barrier
	s_add_i32 s40, s40, 2
	s_add_u32 s38, s38, 0x1000
	s_addc_u32 s39, s39, 0
	s_add_u32 s28, s28, 0x100
	s_addc_u32 s29, s29, 0
	s_cmp_gt_u32 s40, 61
	s_cbranch_scc0 .LBB0_1202
	s_and_b64 vcc, exec, s[10:11]
	s_cbranch_vccz .LBB0_1205
	s_barrier

.LBB0_1263:
	ds_read_b128 v[146:149], v152
	ds_read_b128 v[156:159], v152 offset:1024
	ds_read_b128 v[160:163], v152 offset:2048
	ds_read_b128 v[164:167], v152 offset:3072
	ds_read_b128 v[168:171], v153
	ds_read_b128 v[172:175], v153 offset:1024
	ds_read_b128 v[176:179], v153 offset:2048
	ds_read_b128 v[180:183], v153 offset:3072
	s_add_u32 s22, s20, 0x100
	s_addc_u32 s23, s21, 0
	s_cmp_eq_u32 s46, 12
	s_cselect_b32 s27, s5, s23
	s_cselect_b32 s26, s4, s22
	s_cselect_b32 s25, s19, s15
	s_cselect_b32 s24, s18, s6
	v_lshl_add_u64 v[184:185], s[20:21], 0, v[136:137]
	s_add_i32 m0, s17, 0xc000
	s_nop 0
	global_load_lds_dwordx4 v[184:185], off
	v_lshl_add_u64 v[184:185], s[20:21], 0, v[138:139]
	s_add_i32 m0, s17, 0xe000
	s_nop 0
	global_load_lds_dwordx4 v[184:185], off
	ds_read_b128 v[184:187], v154
	ds_read_b128 v[188:191], v154 offset:1024
	ds_read_b128 v[192:195], v154 offset:2048
	ds_read_b128 v[196:199], v154 offset:3072
	ds_read_b128 v[200:203], v154 offset:4096
	ds_read_b128 v[204:207], v154 offset:5120
	ds_read_b128 v[208:211], v154 offset:6144
	ds_read_b128 v[212:215], v154 offset:7168
	s_waitcnt vmcnt(8)
	s_waitcnt lgkmcnt(0)
	s_barrier
	s_waitcnt lgkmcnt(0)
	v_mfma_f32_16x16x32_bf16 v[124:127], v[146:149], v[184:187], v[124:127]
	v_mfma_f32_16x16x32_bf16 v[124:127], v[156:159], v[188:191], v[124:127]
	v_mfma_f32_16x16x32_bf16 v[120:123], v[160:163], v[184:187], v[120:123]
	v_mfma_f32_16x16x32_bf16 v[120:123], v[164:167], v[188:191], v[120:123]
	v_mfma_f32_16x16x32_bf16 v[112:115], v[146:149], v[192:195], v[112:115]
	v_mfma_f32_16x16x32_bf16 v[112:115], v[156:159], v[196:199], v[112:115]
	v_mfma_f32_16x16x32_bf16 v[104:107], v[160:163], v[192:195], v[104:107]
	v_mfma_f32_16x16x32_bf16 v[104:107], v[164:167], v[196:199], v[104:107]
	v_mfma_f32_16x16x32_bf16 v[96:99], v[146:149], v[200:203], v[96:99]
	v_mfma_f32_16x16x32_bf16 v[96:99], v[156:159], v[204:207], v[96:99]
	v_mfma_f32_16x16x32_bf16 v[88:91], v[160:163], v[200:203], v[88:91]
	v_mfma_f32_16x16x32_bf16 v[88:91], v[164:167], v[204:207], v[88:91]
	v_mfma_f32_16x16x32_bf16 v[80:83], v[146:149], v[208:211], v[80:83]
	v_mfma_f32_16x16x32_bf16 v[80:83], v[156:159], v[212:215], v[80:83]
	v_mfma_f32_16x16x32_bf16 v[72:75], v[160:163], v[208:211], v[72:75]
	v_mfma_f32_16x16x32_bf16 v[72:75], v[164:167], v[212:215], v[72:75]
	v_mfma_f32_16x16x32_bf16 v[116:119], v[168:171], v[184:187], v[116:119]
	v_mfma_f32_16x16x32_bf16 v[116:119], v[172:175], v[188:191], v[116:119]
	v_mfma_f32_16x16x32_bf16 v[108:111], v[176:179], v[184:187], v[108:111]
	v_mfma_f32_16x16x32_bf16 v[108:111], v[180:183], v[188:191], v[108:111]
	v_mfma_f32_16x16x32_bf16 v[100:103], v[168:171], v[192:195], v[100:103]
	v_mfma_f32_16x16x32_bf16 v[100:103], v[172:175], v[196:199], v[100:103]
	v_mfma_f32_16x16x32_bf16 v[92:95], v[176:179], v[192:195], v[92:95]
	v_mfma_f32_16x16x32_bf16 v[92:95], v[180:183], v[196:199], v[92:95]
	v_mfma_f32_16x16x32_bf16 v[84:87], v[168:171], v[200:203], v[84:87]
	v_mfma_f32_16x16x32_bf16 v[84:87], v[172:175], v[204:207], v[84:87]
	v_mfma_f32_16x16x32_bf16 v[76:79], v[176:179], v[200:203], v[76:79]
	v_mfma_f32_16x16x32_bf16 v[76:79], v[180:183], v[204:207], v[76:79]
	v_mfma_f32_16x16x32_bf16 v[68:71], v[168:171], v[208:211], v[68:71]
	v_mfma_f32_16x16x32_bf16 v[68:71], v[172:175], v[212:215], v[68:71]
	v_mfma_f32_16x16x32_bf16 v[64:67], v[176:179], v[208:211], v[64:67]
	v_mfma_f32_16x16x32_bf16 v[64:67], v[180:183], v[212:215], v[64:67]
	s_barrier
	s_add_i32 s20, s41, s33
	v_lshl_add_u64 v[216:217], s[24:25], 0, v[130:131]
	s_mov_b32 m0, s20
	v_lshl_add_u64 v[218:219], s[24:25], 0, v[134:135]
	global_load_lds_dwordx4 v[216:217], off
	s_add_i32 m0, s20, 0x2000
	s_add_u32 s20, s24, 0x200000
	s_addc_u32 s21, s25, 0
	s_add_i32 s47, s42, s33
	global_load_lds_dwordx4 v[218:219], off
	v_lshl_add_u64 v[184:185], s[20:21], 0, v[130:131]
	s_mov_b32 m0, s47
	v_lshl_add_u64 v[220:221], s[26:27], 0, v[128:129]
	global_load_lds_dwordx4 v[184:185], off
	v_lshl_add_u64 v[184:185], s[20:21], 0, v[134:135]
	s_add_i32 m0, s47, 0x2000
	v_lshl_add_u64 v[222:223], s[26:27], 0, v[132:133]
	global_load_lds_dwordx4 v[184:185], off
	s_mov_b32 m0, s17
	s_nop 0
	global_load_lds_dwordx4 v[220:221], off
	s_mov_b32 m0, s34
	s_nop 0
	global_load_lds_dwordx4 v[222:223], off
	ds_read_b128 v[184:187], v154 offset:16384
	ds_read_b128 v[188:191], v154 offset:17408
	ds_read_b128 v[192:195], v154 offset:18432
	ds_read_b128 v[196:199], v154 offset:19456
	ds_read_b128 v[200:203], v154 offset:20480
	ds_read_b128 v[204:207], v154 offset:21504
	ds_read_b128 v[208:211], v154 offset:22528
	ds_read_b128 v[212:215], v154 offset:23552
	s_waitcnt vmcnt(8)
	s_waitcnt lgkmcnt(0)
	s_barrier
	s_waitcnt lgkmcnt(0)
	v_mfma_f32_16x16x32_bf16 v[60:63], v[146:149], v[184:187], v[60:63]
	v_mfma_f32_16x16x32_bf16 v[60:63], v[156:159], v[188:191], v[60:63]
	v_mfma_f32_16x16x32_bf16 v[56:59], v[160:163], v[184:187], v[56:59]
	v_mfma_f32_16x16x32_bf16 v[56:59], v[164:167], v[188:191], v[56:59]
	v_mfma_f32_16x16x32_bf16 v[48:51], v[146:149], v[192:195], v[48:51]
	v_mfma_f32_16x16x32_bf16 v[48:51], v[156:159], v[196:199], v[48:51]
	v_mfma_f32_16x16x32_bf16 v[40:43], v[160:163], v[192:195], v[40:43]
	v_mfma_f32_16x16x32_bf16 v[40:43], v[164:167], v[196:199], v[40:43]
	v_mfma_f32_16x16x32_bf16 v[32:35], v[146:149], v[200:203], v[32:35]
	v_mfma_f32_16x16x32_bf16 v[32:35], v[156:159], v[204:207], v[32:35]
	v_mfma_f32_16x16x32_bf16 v[24:27], v[160:163], v[200:203], v[24:27]
	v_mfma_f32_16x16x32_bf16 v[24:27], v[164:167], v[204:207], v[24:27]
	v_mfma_f32_16x16x32_bf16 v[16:19], v[146:149], v[208:211], v[16:19]
	v_mfma_f32_16x16x32_bf16 v[16:19], v[156:159], v[212:215], v[16:19]
	v_mfma_f32_16x16x32_bf16 v[8:11], v[160:163], v[208:211], v[8:11]
	v_mfma_f32_16x16x32_bf16 v[8:11], v[164:167], v[212:215], v[8:11]
	v_mfma_f32_16x16x32_bf16 v[52:55], v[168:171], v[184:187], v[52:55]
	v_mfma_f32_16x16x32_bf16 v[52:55], v[172:175], v[188:191], v[52:55]
	v_mfma_f32_16x16x32_bf16 v[44:47], v[176:179], v[184:187], v[44:47]
	v_mfma_f32_16x16x32_bf16 v[44:47], v[180:183], v[188:191], v[44:47]
	v_mfma_f32_16x16x32_bf16 v[36:39], v[168:171], v[192:195], v[36:39]
	v_mfma_f32_16x16x32_bf16 v[36:39], v[172:175], v[196:199], v[36:39]
	v_mfma_f32_16x16x32_bf16 v[28:31], v[176:179], v[192:195], v[28:31]
	v_mfma_f32_16x16x32_bf16 v[28:31], v[180:183], v[196:199], v[28:31]
	v_mfma_f32_16x16x32_bf16 v[20:23], v[168:171], v[200:203], v[20:23]
	v_mfma_f32_16x16x32_bf16 v[20:23], v[172:175], v[204:207], v[20:23]
	v_mfma_f32_16x16x32_bf16 v[12:15], v[176:179], v[200:203], v[12:15]
	v_mfma_f32_16x16x32_bf16 v[12:15], v[180:183], v[204:207], v[12:15]
	v_mfma_f32_16x16x32_bf16 v[4:7], v[168:171], v[208:211], v[4:7]
	v_mfma_f32_16x16x32_bf16 v[4:7], v[172:175], v[212:215], v[4:7]
	v_mfma_f32_16x16x32_bf16 v[0:3], v[176:179], v[208:211], v[0:3]
	v_mfma_f32_16x16x32_bf16 v[0:3], v[180:183], v[212:215], v[0:3]
	s_barrier
	s_add_i32 s47, 0, 0x18000
	v_add_u32_e32 v144, s47, v145
	s_add_i32 s48, 0, 0x1c000
	ds_read_b128 v[146:149], v144
	ds_read_b128 v[156:159], v144 offset:1024
	ds_read_b128 v[160:163], v144 offset:2048
	ds_read_b128 v[164:167], v144 offset:3072
	v_add_u32_e32 v144, s48, v145
	ds_read_b128 v[168:171], v144
	ds_read_b128 v[172:175], v144 offset:1024
	ds_read_b128 v[176:179], v144 offset:2048
	ds_read_b128 v[180:183], v144 offset:3072
	s_add_u32 s20, s26, 0x200000
	s_addc_u32 s21, s27, 0
	s_mov_b32 m0, s35
	v_lshl_add_u64 v[184:185], s[20:21], 0, v[128:129]
	global_load_lds_dwordx4 v[184:185], off
	v_lshl_add_u64 v[184:185], s[20:21], 0, v[132:133]
	s_mov_b32 m0, s36
	s_nop 0
	global_load_lds_dwordx4 v[184:185], off
	ds_read_b128 v[184:187], v154 offset:32768
	ds_read_b128 v[188:191], v154 offset:33792
	ds_read_b128 v[192:195], v154 offset:34816
	ds_read_b128 v[196:199], v154 offset:35840
	ds_read_b128 v[200:203], v154 offset:36864
	ds_read_b128 v[204:207], v154 offset:37888
	ds_read_b128 v[208:211], v154 offset:38912
	ds_read_b128 v[212:215], v154 offset:39936
	s_waitcnt vmcnt(8)
	s_waitcnt lgkmcnt(0)
	s_barrier
	s_waitcnt lgkmcnt(0)
	v_mfma_f32_16x16x32_bf16 v[124:127], v[146:149], v[184:187], v[124:127]
	v_mfma_f32_16x16x32_bf16 v[124:127], v[156:159], v[188:191], v[124:127]
	v_mfma_f32_16x16x32_bf16 v[120:123], v[160:163], v[184:187], v[120:123]
	v_mfma_f32_16x16x32_bf16 v[120:123], v[164:167], v[188:191], v[120:123]
	v_mfma_f32_16x16x32_bf16 v[112:115], v[146:149], v[192:195], v[112:115]
	v_mfma_f32_16x16x32_bf16 v[112:115], v[156:159], v[196:199], v[112:115]
	v_mfma_f32_16x16x32_bf16 v[104:107], v[160:163], v[192:195], v[104:107]
	v_mfma_f32_16x16x32_bf16 v[104:107], v[164:167], v[196:199], v[104:107]
	v_mfma_f32_16x16x32_bf16 v[96:99], v[146:149], v[200:203], v[96:99]
	v_mfma_f32_16x16x32_bf16 v[96:99], v[156:159], v[204:207], v[96:99]
	v_mfma_f32_16x16x32_bf16 v[88:91], v[160:163], v[200:203], v[88:91]
	v_mfma_f32_16x16x32_bf16 v[88:91], v[164:167], v[204:207], v[88:91]
	v_mfma_f32_16x16x32_bf16 v[80:83], v[146:149], v[208:211], v[80:83]
	v_mfma_f32_16x16x32_bf16 v[80:83], v[156:159], v[212:215], v[80:83]
	v_mfma_f32_16x16x32_bf16 v[72:75], v[160:163], v[208:211], v[72:75]
	v_mfma_f32_16x16x32_bf16 v[72:75], v[164:167], v[212:215], v[72:75]
	v_mfma_f32_16x16x32_bf16 v[116:119], v[168:171], v[184:187], v[116:119]
	v_mfma_f32_16x16x32_bf16 v[116:119], v[172:175], v[188:191], v[116:119]
	v_mfma_f32_16x16x32_bf16 v[108:111], v[176:179], v[184:187], v[108:111]
	v_mfma_f32_16x16x32_bf16 v[108:111], v[180:183], v[188:191], v[108:111]
	v_mfma_f32_16x16x32_bf16 v[100:103], v[168:171], v[192:195], v[100:103]
	v_mfma_f32_16x16x32_bf16 v[100:103], v[172:175], v[196:199], v[100:103]
	v_mfma_f32_16x16x32_bf16 v[92:95], v[176:179], v[192:195], v[92:95]
	v_mfma_f32_16x16x32_bf16 v[92:95], v[180:183], v[196:199], v[92:95]
	v_mfma_f32_16x16x32_bf16 v[84:87], v[168:171], v[200:203], v[84:87]
	v_mfma_f32_16x16x32_bf16 v[84:87], v[172:175], v[204:207], v[84:87]
	v_mfma_f32_16x16x32_bf16 v[76:79], v[176:179], v[200:203], v[76:79]
	v_mfma_f32_16x16x32_bf16 v[76:79], v[180:183], v[204:207], v[76:79]
	v_mfma_f32_16x16x32_bf16 v[68:71], v[168:171], v[208:211], v[68:71]
	v_mfma_f32_16x16x32_bf16 v[68:71], v[172:175], v[212:215], v[68:71]
	v_mfma_f32_16x16x32_bf16 v[64:67], v[176:179], v[208:211], v[64:67]
	v_mfma_f32_16x16x32_bf16 v[64:67], v[180:183], v[212:215], v[64:67]
	s_barrier
	s_add_i32 s20, s47, s33
	v_lshl_add_u64 v[184:185], v[216:217], 0, s[12:13]
	s_mov_b32 m0, s20
	s_nop 0
	global_load_lds_dwordx4 v[184:185], off
	s_add_i32 m0, s20, 0x2000
	s_add_u32 s20, s24, 0x200080
	v_lshl_add_u64 v[184:185], v[218:219], 0, s[12:13]
	s_addc_u32 s21, s25, 0
	s_add_i32 s24, s48, s33
	global_load_lds_dwordx4 v[184:185], off
	v_lshl_add_u64 v[184:185], s[20:21], 0, v[130:131]
	s_mov_b32 m0, s24
	s_nop 0
	global_load_lds_dwordx4 v[184:185], off
	v_lshl_add_u64 v[184:185], s[20:21], 0, v[134:135]
	s_add_i32 m0, s24, 0x2000
	s_nop 0
	global_load_lds_dwordx4 v[184:185], off
	v_lshl_add_u64 v[184:185], v[220:221], 0, s[12:13]
	s_mov_b32 m0, s37
	s_nop 0
	global_load_lds_dwordx4 v[184:185], off
	v_lshl_add_u64 v[184:185], v[222:223], 0, s[12:13]
	s_mov_b32 m0, s38
	s_nop 0
	global_load_lds_dwordx4 v[184:185], off
	ds_read_b128 v[184:187], v154 offset:49152
	ds_read_b128 v[188:191], v154 offset:50176
	ds_read_b128 v[192:195], v154 offset:51200
	ds_read_b128 v[196:199], v154 offset:52224
	ds_read_b128 v[200:203], v154 offset:53248
	ds_read_b128 v[204:207], v154 offset:54272
	ds_read_b128 v[208:211], v154 offset:55296
	ds_read_b128 v[212:215], v154 offset:56320
	s_waitcnt vmcnt(8)
	s_waitcnt lgkmcnt(0)
	s_barrier
	s_waitcnt lgkmcnt(0)
	v_mfma_f32_16x16x32_bf16 v[60:63], v[146:149], v[184:187], v[60:63]
	v_mfma_f32_16x16x32_bf16 v[60:63], v[156:159], v[188:191], v[60:63]
	v_mfma_f32_16x16x32_bf16 v[56:59], v[160:163], v[184:187], v[56:59]
	v_mfma_f32_16x16x32_bf16 v[56:59], v[164:167], v[188:191], v[56:59]
	v_mfma_f32_16x16x32_bf16 v[48:51], v[146:149], v[192:195], v[48:51]
	v_mfma_f32_16x16x32_bf16 v[48:51], v[156:159], v[196:199], v[48:51]
	v_mfma_f32_16x16x32_bf16 v[40:43], v[160:163], v[192:195], v[40:43]
	v_mfma_f32_16x16x32_bf16 v[40:43], v[164:167], v[196:199], v[40:43]
	v_mfma_f32_16x16x32_bf16 v[32:35], v[146:149], v[200:203], v[32:35]
	v_mfma_f32_16x16x32_bf16 v[32:35], v[156:159], v[204:207], v[32:35]
	v_mfma_f32_16x16x32_bf16 v[24:27], v[160:163], v[200:203], v[24:27]
	v_mfma_f32_16x16x32_bf16 v[24:27], v[164:167], v[204:207], v[24:27]
	v_mfma_f32_16x16x32_bf16 v[16:19], v[146:149], v[208:211], v[16:19]
	v_mfma_f32_16x16x32_bf16 v[16:19], v[156:159], v[212:215], v[16:19]
	v_mfma_f32_16x16x32_bf16 v[8:11], v[160:163], v[208:211], v[8:11]
	v_mfma_f32_16x16x32_bf16 v[8:11], v[164:167], v[212:215], v[8:11]
	v_mfma_f32_16x16x32_bf16 v[52:55], v[168:171], v[184:187], v[52:55]
	v_mfma_f32_16x16x32_bf16 v[52:55], v[172:175], v[188:191], v[52:55]
	v_mfma_f32_16x16x32_bf16 v[44:47], v[176:179], v[184:187], v[44:47]
	v_mfma_f32_16x16x32_bf16 v[44:47], v[180:183], v[188:191], v[44:47]
	v_mfma_f32_16x16x32_bf16 v[36:39], v[168:171], v[192:195], v[36:39]
	v_mfma_f32_16x16x32_bf16 v[36:39], v[172:175], v[196:199], v[36:39]
	v_mfma_f32_16x16x32_bf16 v[28:31], v[176:179], v[192:195], v[28:31]
	v_mfma_f32_16x16x32_bf16 v[28:31], v[180:183], v[196:199], v[28:31]
	v_mfma_f32_16x16x32_bf16 v[20:23], v[168:171], v[200:203], v[20:23]
	v_mfma_f32_16x16x32_bf16 v[20:23], v[172:175], v[204:207], v[20:23]
	v_mfma_f32_16x16x32_bf16 v[12:15], v[176:179], v[200:203], v[12:15]
	v_mfma_f32_16x16x32_bf16 v[12:15], v[180:183], v[204:207], v[12:15]
	v_mfma_f32_16x16x32_bf16 v[4:7], v[168:171], v[208:211], v[4:7]
	v_mfma_f32_16x16x32_bf16 v[4:7], v[172:175], v[212:215], v[4:7]
	v_mfma_f32_16x16x32_bf16 v[0:3], v[176:179], v[208:211], v[0:3]
	v_mfma_f32_16x16x32_bf16 v[0:3], v[180:183], v[212:215], v[0:3]
	s_barrier
	s_add_i32 s46, s46, 2
	s_add_u32 s6, s6, 0x100
	s_addc_u32 s15, s15, 0
	s_cmp_gt_u32 s46, 13
	s_mov_b64 s[20:21], s[22:23]
	s_cbranch_scc0 .LBB0_1263
	s_and_b64 vcc, exec, s[8:9]
	s_cbranch_vccz .LBB0_1266
	s_barrier

.LBB0_1340:
	v_add_u32_e32 v166, s51, v152
	v_add_u32_e32 v182, s52, v152
	ds_read_b128 v[154:157], v166
	ds_read_b128 v[158:161], v166 offset:1024
	ds_read_b128 v[162:165], v166 offset:2048
	ds_read_b128 v[166:169], v166 offset:3072
	ds_read_b128 v[170:173], v182
	ds_read_b128 v[174:177], v182 offset:1024
	ds_read_b128 v[178:181], v182 offset:2048
	ds_read_b128 v[182:185], v182 offset:3072
	s_add_u32 s30, s10, s28
	s_addc_u32 s31, s11, s29
	s_cmp_eq_u32 s58, 60
	s_cselect_b32 s35, s23, s31
	s_cselect_b32 s34, s54, s30
	s_cselect_b32 s31, s21, s57
	s_cselect_b32 s30, s55, s56
	v_lshl_add_u64 v[186:187], s[10:11], 0, v[146:147]
	s_add_i32 m0, s44, 0xc000
	s_nop 0
	global_load_lds_dwordx4 v[186:187], off
	v_lshl_add_u64 v[186:187], s[10:11], 0, v[144:145]
	s_add_i32 m0, s44, 0xe000
	s_nop 0
	global_load_lds_dwordx4 v[186:187], off
	ds_read_b128 v[186:189], v153
	ds_read_b128 v[190:193], v153 offset:1024
	ds_read_b128 v[194:197], v153 offset:2048
	ds_read_b128 v[198:201], v153 offset:3072
	ds_read_b128 v[202:205], v153 offset:4096
	ds_read_b128 v[206:209], v153 offset:5120
	ds_read_b128 v[210:213], v153 offset:6144
	ds_read_b128 v[214:217], v153 offset:7168
	s_waitcnt vmcnt(8)
	s_waitcnt lgkmcnt(0)
	s_barrier
	s_waitcnt lgkmcnt(0)
	v_mfma_f32_16x16x32_bf16 v[124:127], v[154:157], v[186:189], v[124:127]
	v_mfma_f32_16x16x32_bf16 v[124:127], v[158:161], v[190:193], v[124:127]
	v_mfma_f32_16x16x32_bf16 v[120:123], v[162:165], v[186:189], v[120:123]
	v_mfma_f32_16x16x32_bf16 v[120:123], v[166:169], v[190:193], v[120:123]
	v_mfma_f32_16x16x32_bf16 v[108:111], v[154:157], v[194:197], v[108:111]
	v_mfma_f32_16x16x32_bf16 v[108:111], v[158:161], v[198:201], v[108:111]
	v_mfma_f32_16x16x32_bf16 v[104:107], v[162:165], v[194:197], v[104:107]
	v_mfma_f32_16x16x32_bf16 v[104:107], v[166:169], v[198:201], v[104:107]
	v_mfma_f32_16x16x32_bf16 v[92:95], v[154:157], v[202:205], v[92:95]
	v_mfma_f32_16x16x32_bf16 v[92:95], v[158:161], v[206:209], v[92:95]
	v_mfma_f32_16x16x32_bf16 v[88:91], v[162:165], v[202:205], v[88:91]
	v_mfma_f32_16x16x32_bf16 v[88:91], v[166:169], v[206:209], v[88:91]
	v_mfma_f32_16x16x32_bf16 v[76:79], v[154:157], v[210:213], v[76:79]
	v_mfma_f32_16x16x32_bf16 v[76:79], v[158:161], v[214:217], v[76:79]
	v_mfma_f32_16x16x32_bf16 v[72:75], v[162:165], v[210:213], v[72:75]
	v_mfma_f32_16x16x32_bf16 v[72:75], v[166:169], v[214:217], v[72:75]
	v_mfma_f32_16x16x32_bf16 v[116:119], v[170:173], v[186:189], v[116:119]
	v_mfma_f32_16x16x32_bf16 v[116:119], v[174:177], v[190:193], v[116:119]
	v_mfma_f32_16x16x32_bf16 v[112:115], v[178:181], v[186:189], v[112:115]
	v_mfma_f32_16x16x32_bf16 v[112:115], v[182:185], v[190:193], v[112:115]
	v_mfma_f32_16x16x32_bf16 v[100:103], v[170:173], v[194:197], v[100:103]
	v_mfma_f32_16x16x32_bf16 v[100:103], v[174:177], v[198:201], v[100:103]
	v_mfma_f32_16x16x32_bf16 v[96:99], v[178:181], v[194:197], v[96:99]
	v_mfma_f32_16x16x32_bf16 v[96:99], v[182:185], v[198:201], v[96:99]
	v_mfma_f32_16x16x32_bf16 v[84:87], v[170:173], v[202:205], v[84:87]
	v_mfma_f32_16x16x32_bf16 v[84:87], v[174:177], v[206:209], v[84:87]
	v_mfma_f32_16x16x32_bf16 v[80:83], v[178:181], v[202:205], v[80:83]
	v_mfma_f32_16x16x32_bf16 v[80:83], v[182:185], v[206:209], v[80:83]
	v_mfma_f32_16x16x32_bf16 v[68:71], v[170:173], v[210:213], v[68:71]
	v_mfma_f32_16x16x32_bf16 v[68:71], v[174:177], v[214:217], v[68:71]
	v_mfma_f32_16x16x32_bf16 v[64:67], v[178:181], v[210:213], v[64:67]
	v_mfma_f32_16x16x32_bf16 v[64:67], v[182:185], v[214:217], v[64:67]
	s_barrier
	s_add_i32 s59, s51, s43
	v_lshl_add_u64 v[218:219], s[30:31], 0, v[130:131]
	s_mov_b32 m0, s59
	v_lshl_add_u64 v[220:221], s[30:31], 0, v[134:135]
	global_load_lds_dwordx4 v[218:219], off
	s_add_i32 m0, s59, 0x2000
	s_add_u32 s60, s30, 0x100000
	s_addc_u32 s61, s31, 0
	s_add_i32 s59, s52, s43
	global_load_lds_dwordx4 v[220:221], off
	v_lshl_add_u64 v[186:187], s[60:61], 0, v[130:131]
	s_mov_b32 m0, s59
	v_lshl_add_u64 v[222:223], s[34:35], 0, v[128:129]
	global_load_lds_dwordx4 v[186:187], off
	v_lshl_add_u64 v[186:187], s[60:61], 0, v[134:135]
	s_add_i32 m0, s59, 0x2000
	v_lshl_add_u64 v[224:225], s[34:35], 0, v[132:133]
	global_load_lds_dwordx4 v[186:187], off
	s_mov_b32 m0, s44
	s_nop 0
	global_load_lds_dwordx4 v[222:223], off
	s_mov_b32 m0, s45
	s_nop 0
	global_load_lds_dwordx4 v[224:225], off
	ds_read_b128 v[186:189], v153 offset:16384
	ds_read_b128 v[190:193], v153 offset:17408
	ds_read_b128 v[194:197], v153 offset:18432
	ds_read_b128 v[198:201], v153 offset:19456
	ds_read_b128 v[202:205], v153 offset:20480
	ds_read_b128 v[206:209], v153 offset:21504
	ds_read_b128 v[210:213], v153 offset:22528
	ds_read_b128 v[214:217], v153 offset:23552
	s_waitcnt vmcnt(8)
	s_waitcnt lgkmcnt(0)
	s_barrier
	s_waitcnt lgkmcnt(0)
	v_mfma_f32_16x16x32_bf16 v[60:63], v[154:157], v[186:189], v[60:63]
	v_mfma_f32_16x16x32_bf16 v[60:63], v[158:161], v[190:193], v[60:63]
	v_mfma_f32_16x16x32_bf16 v[56:59], v[162:165], v[186:189], v[56:59]
	v_mfma_f32_16x16x32_bf16 v[56:59], v[166:169], v[190:193], v[56:59]
	v_mfma_f32_16x16x32_bf16 v[44:47], v[154:157], v[194:197], v[44:47]
	v_mfma_f32_16x16x32_bf16 v[44:47], v[158:161], v[198:201], v[44:47]
	v_mfma_f32_16x16x32_bf16 v[40:43], v[162:165], v[194:197], v[40:43]
	v_mfma_f32_16x16x32_bf16 v[40:43], v[166:169], v[198:201], v[40:43]
	v_mfma_f32_16x16x32_bf16 v[28:31], v[154:157], v[202:205], v[28:31]
	v_mfma_f32_16x16x32_bf16 v[28:31], v[158:161], v[206:209], v[28:31]
	v_mfma_f32_16x16x32_bf16 v[24:27], v[162:165], v[202:205], v[24:27]
	v_mfma_f32_16x16x32_bf16 v[24:27], v[166:169], v[206:209], v[24:27]
	v_mfma_f32_16x16x32_bf16 v[12:15], v[154:157], v[210:213], v[12:15]
	v_mfma_f32_16x16x32_bf16 v[12:15], v[158:161], v[214:217], v[12:15]
	v_mfma_f32_16x16x32_bf16 v[8:11], v[162:165], v[210:213], v[8:11]
	v_mfma_f32_16x16x32_bf16 v[8:11], v[166:169], v[214:217], v[8:11]
	v_mfma_f32_16x16x32_bf16 v[52:55], v[170:173], v[186:189], v[52:55]
	v_mfma_f32_16x16x32_bf16 v[52:55], v[174:177], v[190:193], v[52:55]
	v_mfma_f32_16x16x32_bf16 v[48:51], v[178:181], v[186:189], v[48:51]
	v_mfma_f32_16x16x32_bf16 v[48:51], v[182:185], v[190:193], v[48:51]
	v_mfma_f32_16x16x32_bf16 v[36:39], v[170:173], v[194:197], v[36:39]
	v_mfma_f32_16x16x32_bf16 v[36:39], v[174:177], v[198:201], v[36:39]
	v_mfma_f32_16x16x32_bf16 v[32:35], v[178:181], v[194:197], v[32:35]
	v_mfma_f32_16x16x32_bf16 v[32:35], v[182:185], v[198:201], v[32:35]
	v_mfma_f32_16x16x32_bf16 v[20:23], v[170:173], v[202:205], v[20:23]
	v_mfma_f32_16x16x32_bf16 v[20:23], v[174:177], v[206:209], v[20:23]
	v_mfma_f32_16x16x32_bf16 v[16:19], v[178:181], v[202:205], v[16:19]
	v_mfma_f32_16x16x32_bf16 v[16:19], v[182:185], v[206:209], v[16:19]
	v_mfma_f32_16x16x32_bf16 v[4:7], v[170:173], v[210:213], v[4:7]
	v_mfma_f32_16x16x32_bf16 v[4:7], v[174:177], v[214:217], v[4:7]
	v_mfma_f32_16x16x32_bf16 v[0:3], v[178:181], v[210:213], v[0:3]
	v_mfma_f32_16x16x32_bf16 v[0:3], v[182:185], v[214:217], v[0:3]
	s_barrier
	s_add_i32 s59, 0, 0x18000
	s_add_i32 s60, 0, 0x1c000
	v_add_u32_e32 v166, s59, v152
	v_add_u32_e32 v182, s60, v152
	ds_read_b128 v[154:157], v166
	ds_read_b128 v[158:161], v166 offset:1024
	ds_read_b128 v[162:165], v166 offset:2048
	ds_read_b128 v[166:169], v166 offset:3072
	ds_read_b128 v[170:173], v182
	ds_read_b128 v[174:177], v182 offset:1024
	ds_read_b128 v[178:181], v182 offset:2048
	ds_read_b128 v[182:185], v182 offset:3072
	s_add_u32 s34, s34, 0x100000
	s_addc_u32 s35, s35, 0
	s_mov_b32 m0, s46
	v_lshl_add_u64 v[186:187], s[34:35], 0, v[128:129]
	global_load_lds_dwordx4 v[186:187], off
	v_lshl_add_u64 v[186:187], s[34:35], 0, v[132:133]
	s_mov_b32 m0, s47
	s_nop 0
	global_load_lds_dwordx4 v[186:187], off
	ds_read_b128 v[186:189], v153 offset:32768
	ds_read_b128 v[190:193], v153 offset:33792
	ds_read_b128 v[194:197], v153 offset:34816
	ds_read_b128 v[198:201], v153 offset:35840
	ds_read_b128 v[202:205], v153 offset:36864
	ds_read_b128 v[206:209], v153 offset:37888
	ds_read_b128 v[210:213], v153 offset:38912
	ds_read_b128 v[214:217], v153 offset:39936
	s_waitcnt vmcnt(8)
	s_waitcnt lgkmcnt(0)
	s_barrier
	s_waitcnt lgkmcnt(0)
	v_mfma_f32_16x16x32_bf16 v[124:127], v[154:157], v[186:189], v[124:127]
	v_mfma_f32_16x16x32_bf16 v[124:127], v[158:161], v[190:193], v[124:127]
	v_mfma_f32_16x16x32_bf16 v[120:123], v[162:165], v[186:189], v[120:123]
	v_mfma_f32_16x16x32_bf16 v[120:123], v[166:169], v[190:193], v[120:123]
	v_mfma_f32_16x16x32_bf16 v[108:111], v[154:157], v[194:197], v[108:111]
	v_mfma_f32_16x16x32_bf16 v[108:111], v[158:161], v[198:201], v[108:111]
	v_mfma_f32_16x16x32_bf16 v[104:107], v[162:165], v[194:197], v[104:107]
	v_mfma_f32_16x16x32_bf16 v[104:107], v[166:169], v[198:201], v[104:107]
	v_mfma_f32_16x16x32_bf16 v[92:95], v[154:157], v[202:205], v[92:95]
	v_mfma_f32_16x16x32_bf16 v[92:95], v[158:161], v[206:209], v[92:95]
	v_mfma_f32_16x16x32_bf16 v[88:91], v[162:165], v[202:205], v[88:91]
	v_mfma_f32_16x16x32_bf16 v[88:91], v[166:169], v[206:209], v[88:91]
	v_mfma_f32_16x16x32_bf16 v[76:79], v[154:157], v[210:213], v[76:79]
	v_mfma_f32_16x16x32_bf16 v[76:79], v[158:161], v[214:217], v[76:79]
	v_mfma_f32_16x16x32_bf16 v[72:75], v[162:165], v[210:213], v[72:75]
	v_mfma_f32_16x16x32_bf16 v[72:75], v[166:169], v[214:217], v[72:75]
	v_mfma_f32_16x16x32_bf16 v[116:119], v[170:173], v[186:189], v[116:119]
	v_mfma_f32_16x16x32_bf16 v[116:119], v[174:177], v[190:193], v[116:119]
	v_mfma_f32_16x16x32_bf16 v[112:115], v[178:181], v[186:189], v[112:115]
	v_mfma_f32_16x16x32_bf16 v[112:115], v[182:185], v[190:193], v[112:115]
	v_mfma_f32_16x16x32_bf16 v[100:103], v[170:173], v[194:197], v[100:103]
	v_mfma_f32_16x16x32_bf16 v[100:103], v[174:177], v[198:201], v[100:103]
	v_mfma_f32_16x16x32_bf16 v[96:99], v[178:181], v[194:197], v[96:99]
	v_mfma_f32_16x16x32_bf16 v[96:99], v[182:185], v[198:201], v[96:99]
	v_mfma_f32_16x16x32_bf16 v[84:87], v[170:173], v[202:205], v[84:87]
	v_mfma_f32_16x16x32_bf16 v[84:87], v[174:177], v[206:209], v[84:87]
	v_mfma_f32_16x16x32_bf16 v[80:83], v[178:181], v[202:205], v[80:83]
	v_mfma_f32_16x16x32_bf16 v[80:83], v[182:185], v[206:209], v[80:83]
	v_mfma_f32_16x16x32_bf16 v[68:71], v[170:173], v[210:213], v[68:71]
	v_mfma_f32_16x16x32_bf16 v[68:71], v[174:177], v[214:217], v[68:71]
	v_mfma_f32_16x16x32_bf16 v[64:67], v[178:181], v[210:213], v[64:67]
	v_mfma_f32_16x16x32_bf16 v[64:67], v[182:185], v[214:217], v[64:67]
	s_barrier
	s_add_i32 s34, s59, s43
	v_lshl_add_u64 v[186:187], v[218:219], 0, s[14:15]
	s_mov_b32 m0, s34
	s_nop 0
	global_load_lds_dwordx4 v[186:187], off
	s_add_i32 m0, s34, 0x2000
	s_add_u32 s30, s30, 0x100080
	v_lshl_add_u64 v[186:187], v[220:221], 0, s[14:15]
	s_addc_u32 s31, s31, 0
	s_add_i32 s34, s60, s43
	global_load_lds_dwordx4 v[186:187], off
	v_lshl_add_u64 v[186:187], s[30:31], 0, v[130:131]
	s_mov_b32 m0, s34
	s_nop 0
	global_load_lds_dwordx4 v[186:187], off
	v_lshl_add_u64 v[186:187], s[30:31], 0, v[134:135]
	s_add_i32 m0, s34, 0x2000
	s_nop 0
	global_load_lds_dwordx4 v[186:187], off
	v_lshl_add_u64 v[186:187], v[222:223], 0, s[16:17]
	s_mov_b32 m0, s49
	s_nop 0
	global_load_lds_dwordx4 v[186:187], off
	v_lshl_add_u64 v[186:187], v[224:225], 0, s[16:17]
	s_mov_b32 m0, s50
	s_nop 0
	global_load_lds_dwordx4 v[186:187], off
	ds_read_b128 v[186:189], v153 offset:49152
	ds_read_b128 v[190:193], v153 offset:50176
	ds_read_b128 v[194:197], v153 offset:51200
	ds_read_b128 v[198:201], v153 offset:52224
	ds_read_b128 v[202:205], v153 offset:53248
	ds_read_b128 v[206:209], v153 offset:54272
	ds_read_b128 v[210:213], v153 offset:55296
	ds_read_b128 v[214:217], v153 offset:56320
	s_waitcnt vmcnt(8)
	s_waitcnt lgkmcnt(0)
	s_barrier
	s_waitcnt lgkmcnt(0)
	v_mfma_f32_16x16x32_bf16 v[60:63], v[154:157], v[186:189], v[60:63]
	v_mfma_f32_16x16x32_bf16 v[60:63], v[158:161], v[190:193], v[60:63]
	v_mfma_f32_16x16x32_bf16 v[56:59], v[162:165], v[186:189], v[56:59]
	v_mfma_f32_16x16x32_bf16 v[56:59], v[166:169], v[190:193], v[56:59]
	v_mfma_f32_16x16x32_bf16 v[44:47], v[154:157], v[194:197], v[44:47]
	v_mfma_f32_16x16x32_bf16 v[44:47], v[158:161], v[198:201], v[44:47]
	v_mfma_f32_16x16x32_bf16 v[40:43], v[162:165], v[194:197], v[40:43]
	v_mfma_f32_16x16x32_bf16 v[40:43], v[166:169], v[198:201], v[40:43]
	v_mfma_f32_16x16x32_bf16 v[28:31], v[154:157], v[202:205], v[28:31]
	v_mfma_f32_16x16x32_bf16 v[28:31], v[158:161], v[206:209], v[28:31]
	v_mfma_f32_16x16x32_bf16 v[24:27], v[162:165], v[202:205], v[24:27]
	v_mfma_f32_16x16x32_bf16 v[24:27], v[166:169], v[206:209], v[24:27]
	v_mfma_f32_16x16x32_bf16 v[12:15], v[154:157], v[210:213], v[12:15]
	v_mfma_f32_16x16x32_bf16 v[12:15], v[158:161], v[214:217], v[12:15]
	v_mfma_f32_16x16x32_bf16 v[8:11], v[162:165], v[210:213], v[8:11]
	v_mfma_f32_16x16x32_bf16 v[8:11], v[166:169], v[214:217], v[8:11]
	v_mfma_f32_16x16x32_bf16 v[52:55], v[170:173], v[186:189], v[52:55]
	v_mfma_f32_16x16x32_bf16 v[52:55], v[174:177], v[190:193], v[52:55]
	v_mfma_f32_16x16x32_bf16 v[48:51], v[178:181], v[186:189], v[48:51]
	v_mfma_f32_16x16x32_bf16 v[48:51], v[182:185], v[190:193], v[48:51]
	v_mfma_f32_16x16x32_bf16 v[36:39], v[170:173], v[194:197], v[36:39]
	v_mfma_f32_16x16x32_bf16 v[36:39], v[174:177], v[198:201], v[36:39]
	v_mfma_f32_16x16x32_bf16 v[32:35], v[178:181], v[194:197], v[32:35]
	v_mfma_f32_16x16x32_bf16 v[32:35], v[182:185], v[198:201], v[32:35]
	v_mfma_f32_16x16x32_bf16 v[20:23], v[170:173], v[202:205], v[20:23]
	v_mfma_f32_16x16x32_bf16 v[20:23], v[174:177], v[206:209], v[20:23]
	v_mfma_f32_16x16x32_bf16 v[16:19], v[178:181], v[202:205], v[16:19]
	v_mfma_f32_16x16x32_bf16 v[16:19], v[182:185], v[206:209], v[16:19]
	v_mfma_f32_16x16x32_bf16 v[4:7], v[170:173], v[210:213], v[4:7]
	v_mfma_f32_16x16x32_bf16 v[4:7], v[174:177], v[214:217], v[4:7]
	v_mfma_f32_16x16x32_bf16 v[0:3], v[178:181], v[210:213], v[0:3]
	v_mfma_f32_16x16x32_bf16 v[0:3], v[182:185], v[214:217], v[0:3]
	s_barrier
	s_add_i32 s58, s58, 2
	s_add_u32 s56, s56, 0x100
	s_addc_u32 s57, s57, 0
	s_add_u32 s28, s28, 0x1000
	s_addc_u32 s29, s29, 0
	v_lshl_add_u64 v[146:147], v[146:147], 0, s[18:19]
	s_cmp_gt_u32 s58, 61
	v_lshl_add_u64 v[144:145], v[144:145], 0, s[18:19]
	s_cbranch_scc0 .LBB0_1340
	s_andn2_b64 vcc, exec, s[4:5]
	s_cbranch_vccnz .LBB0_1332
	v_mov_b32_e32 v0, 0
	s_mov_b32 s7, s20
	s_mov_b32 s6, s22
	s_mov_b64 s[8:9], s[26:27]
	s_mov_b64 s[10:11], s[24:25]
	s_mov_b32 s48, s53
	v_mov_b32_e32 v1, v0
	v_mov_b32_e32 v2, v0
	v_mov_b32_e32 v3, v0
	v_mov_b32_e32 v4, v0
	v_mov_b32_e32 v5, v0
	v_mov_b32_e32 v6, v0
	v_mov_b32_e32 v7, v0
	v_mov_b32_e32 v16, v0
	v_mov_b32_e32 v17, v0
	v_mov_b32_e32 v18, v0
	v_mov_b32_e32 v19, v0
	v_mov_b32_e32 v20, v0
	v_mov_b32_e32 v21, v0
	v_mov_b32_e32 v22, v0
	v_mov_b32_e32 v23, v0
	v_mov_b32_e32 v32, v0
	v_mov_b32_e32 v33, v0
	v_mov_b32_e32 v34, v0
	v_mov_b32_e32 v35, v0
	v_mov_b32_e32 v36, v0
	v_mov_b32_e32 v37, v0
	v_mov_b32_e32 v38, v0
	v_mov_b32_e32 v39, v0
	v_mov_b32_e32 v48, v0
	v_mov_b32_e32 v49, v0
	v_mov_b32_e32 v50, v0
	v_mov_b32_e32 v51, v0
	v_mov_b32_e32 v52, v0
	v_mov_b32_e32 v53, v0
	v_mov_b32_e32 v54, v0
	v_mov_b32_e32 v55, v0
	v_mov_b32_e32 v8, v0
	v_mov_b32_e32 v9, v0
	v_mov_b32_e32 v10, v0
	v_mov_b32_e32 v11, v0
	v_mov_b32_e32 v12, v0
	v_mov_b32_e32 v13, v0
	v_mov_b32_e32 v14, v0
	v_mov_b32_e32 v15, v0
	v_mov_b32_e32 v24, v0
	v_mov_b32_e32 v25, v0
	v_mov_b32_e32 v26, v0
	v_mov_b32_e32 v27, v0
	v_mov_b32_e32 v28, v0
	v_mov_b32_e32 v29, v0
	v_mov_b32_e32 v30, v0
	v_mov_b32_e32 v31, v0
	v_mov_b32_e32 v40, v0
	v_mov_b32_e32 v41, v0
	v_mov_b32_e32 v42, v0
	v_mov_b32_e32 v43, v0
	v_mov_b32_e32 v44, v0
	v_mov_b32_e32 v45, v0
	v_mov_b32_e32 v46, v0
	v_mov_b32_e32 v47, v0
	v_mov_b32_e32 v56, v0
	v_mov_b32_e32 v57, v0
	v_mov_b32_e32 v58, v0
	v_mov_b32_e32 v59, v0
	v_mov_b32_e32 v60, v0
	v_mov_b32_e32 v61, v0
	v_mov_b32_e32 v62, v0
	v_mov_b32_e32 v63, v0
	v_mov_b32_e32 v64, v0
	v_mov_b32_e32 v65, v0
	v_mov_b32_e32 v66, v0
	v_mov_b32_e32 v67, v0
	v_mov_b32_e32 v68, v0
	v_mov_b32_e32 v69, v0
	v_mov_b32_e32 v70, v0
	v_mov_b32_e32 v71, v0
	v_mov_b32_e32 v80, v0
	v_mov_b32_e32 v81, v0
	v_mov_b32_e32 v82, v0
	v_mov_b32_e32 v83, v0
	v_mov_b32_e32 v84, v0
	v_mov_b32_e32 v85, v0
	v_mov_b32_e32 v86, v0
	v_mov_b32_e32 v87, v0
	v_mov_b32_e32 v96, v0
	v_mov_b32_e32 v97, v0
	v_mov_b32_e32 v98, v0
	v_mov_b32_e32 v99, v0
	v_mov_b32_e32 v100, v0
	v_mov_b32_e32 v101, v0
	v_mov_b32_e32 v102, v0
	v_mov_b32_e32 v103, v0
	v_mov_b32_e32 v112, v0
	v_mov_b32_e32 v113, v0
	v_mov_b32_e32 v114, v0
	v_mov_b32_e32 v115, v0
	v_mov_b32_e32 v116, v0
	v_mov_b32_e32 v117, v0
	v_mov_b32_e32 v118, v0
	v_mov_b32_e32 v119, v0
	v_mov_b32_e32 v72, v0
	v_mov_b32_e32 v73, v0
	v_mov_b32_e32 v74, v0
	v_mov_b32_e32 v75, v0
	v_mov_b32_e32 v76, v0
	v_mov_b32_e32 v77, v0
	v_mov_b32_e32 v78, v0
	v_mov_b32_e32 v79, v0
	v_mov_b32_e32 v88, v0
	v_mov_b32_e32 v89, v0
	v_mov_b32_e32 v90, v0
	v_mov_b32_e32 v91, v0
	v_mov_b32_e32 v92, v0
	v_mov_b32_e32 v93, v0
	v_mov_b32_e32 v94, v0
	v_mov_b32_e32 v95, v0
	v_mov_b32_e32 v104, v0
	v_mov_b32_e32 v105, v0
	v_mov_b32_e32 v106, v0
	v_mov_b32_e32 v107, v0
	v_mov_b32_e32 v108, v0
	v_mov_b32_e32 v109, v0
	v_mov_b32_e32 v110, v0
	v_mov_b32_e32 v111, v0
	v_mov_b32_e32 v120, v0
	v_mov_b32_e32 v121, v0
	v_mov_b32_e32 v122, v0
	v_mov_b32_e32 v123, v0
	v_mov_b32_e32 v124, v0
	v_mov_b32_e32 v125, v0
	v_mov_b32_e32 v126, v0
	v_mov_b32_e32 v127, v0
	s_branch .LBB0_1332

.LBB0_1435:
	ds_read_b128 v[128:131], v180
	ds_read_b128 v[132:135], v180 offset:1024
	ds_read_b128 v[136:139], v180 offset:2048
	ds_read_b128 v[140:143], v180 offset:3072
	ds_read_b128 v[144:147], v181
	ds_read_b128 v[148:151], v181 offset:1024
	ds_read_b128 v[170:173], v181 offset:2048
	ds_read_b128 v[174:177], v181 offset:3072
	s_add_u32 s26, s24, 0xfffc0080
	s_addc_u32 s27, s25, -1
	s_cmp_eq_u32 s35, 12
	s_cselect_b32 s29, s1, s27
	s_cselect_b32 s28, s19, s26
	s_cselect_b32 s27, s17, s34
	s_cselect_b32 s26, s30, s31
	v_lshl_add_u64 v[184:185], s[24:25], 0, v[162:163]
	s_add_i32 m0, s40, 0xc000
	s_nop 0
	global_load_lds_dwordx4 v[184:185], off
	v_lshl_add_u64 v[184:185], s[24:25], 0, v[164:165]
	s_add_i32 m0, s40, 0xe000
	s_nop 0
	global_load_lds_dwordx4 v[184:185], off
	ds_read_b128 v[184:187], v182
	ds_read_b128 v[188:191], v182 offset:1024
	ds_read_b128 v[192:195], v182 offset:2048
	ds_read_b128 v[196:199], v182 offset:3072
	ds_read_b128 v[200:203], v182 offset:4096
	ds_read_b128 v[204:207], v182 offset:5120
	ds_read_b128 v[208:211], v182 offset:6144
	ds_read_b128 v[212:215], v182 offset:7168
	s_waitcnt vmcnt(8)
	s_waitcnt lgkmcnt(0)
	s_barrier
	s_waitcnt lgkmcnt(0)
	v_mfma_f32_16x16x32_bf16 v[124:127], v[128:131], v[184:187], v[124:127]
	v_mfma_f32_16x16x32_bf16 v[124:127], v[132:135], v[188:191], v[124:127]
	v_mfma_f32_16x16x32_bf16 v[120:123], v[136:139], v[184:187], v[120:123]
	v_mfma_f32_16x16x32_bf16 v[120:123], v[140:143], v[188:191], v[120:123]
	v_mfma_f32_16x16x32_bf16 v[108:111], v[128:131], v[192:195], v[108:111]
	v_mfma_f32_16x16x32_bf16 v[108:111], v[132:135], v[196:199], v[108:111]
	v_mfma_f32_16x16x32_bf16 v[104:107], v[136:139], v[192:195], v[104:107]
	v_mfma_f32_16x16x32_bf16 v[104:107], v[140:143], v[196:199], v[104:107]
	v_mfma_f32_16x16x32_bf16 v[92:95], v[128:131], v[200:203], v[92:95]
	v_mfma_f32_16x16x32_bf16 v[92:95], v[132:135], v[204:207], v[92:95]
	v_mfma_f32_16x16x32_bf16 v[88:91], v[136:139], v[200:203], v[88:91]
	v_mfma_f32_16x16x32_bf16 v[88:91], v[140:143], v[204:207], v[88:91]
	v_mfma_f32_16x16x32_bf16 v[76:79], v[128:131], v[208:211], v[76:79]
	v_mfma_f32_16x16x32_bf16 v[76:79], v[132:135], v[212:215], v[76:79]
	v_mfma_f32_16x16x32_bf16 v[72:75], v[136:139], v[208:211], v[72:75]
	v_mfma_f32_16x16x32_bf16 v[72:75], v[140:143], v[212:215], v[72:75]
	v_mfma_f32_16x16x32_bf16 v[116:119], v[144:147], v[184:187], v[116:119]
	v_mfma_f32_16x16x32_bf16 v[116:119], v[148:151], v[188:191], v[116:119]
	v_mfma_f32_16x16x32_bf16 v[112:115], v[170:173], v[184:187], v[112:115]
	v_mfma_f32_16x16x32_bf16 v[112:115], v[174:177], v[188:191], v[112:115]
	v_mfma_f32_16x16x32_bf16 v[100:103], v[144:147], v[192:195], v[100:103]
	v_mfma_f32_16x16x32_bf16 v[100:103], v[148:151], v[196:199], v[100:103]
	v_mfma_f32_16x16x32_bf16 v[96:99], v[170:173], v[192:195], v[96:99]
	v_mfma_f32_16x16x32_bf16 v[96:99], v[174:177], v[196:199], v[96:99]
	v_mfma_f32_16x16x32_bf16 v[84:87], v[144:147], v[200:203], v[84:87]
	v_mfma_f32_16x16x32_bf16 v[84:87], v[148:151], v[204:207], v[84:87]
	v_mfma_f32_16x16x32_bf16 v[80:83], v[170:173], v[200:203], v[80:83]
	v_mfma_f32_16x16x32_bf16 v[80:83], v[174:177], v[204:207], v[80:83]
	v_mfma_f32_16x16x32_bf16 v[68:71], v[144:147], v[208:211], v[68:71]
	v_mfma_f32_16x16x32_bf16 v[68:71], v[148:151], v[212:215], v[68:71]
	v_mfma_f32_16x16x32_bf16 v[64:67], v[170:173], v[208:211], v[64:67]
	v_mfma_f32_16x16x32_bf16 v[64:67], v[174:177], v[212:215], v[64:67]
	s_barrier
	s_add_i32 s54, s50, s39
	v_lshl_add_u64 v[216:217], s[26:27], 0, v[154:155]
	s_mov_b32 m0, s54
	v_lshl_add_u64 v[218:219], s[26:27], 0, v[158:159]
	global_load_lds_dwordx4 v[216:217], off
	s_add_i32 m0, s54, 0x2000
	s_add_u32 s54, s26, 0x100000
	s_addc_u32 s55, s27, 0
	s_add_i32 s56, s51, s39
	global_load_lds_dwordx4 v[218:219], off
	v_lshl_add_u64 v[184:185], s[54:55], 0, v[154:155]
	s_mov_b32 m0, s56
	v_lshl_add_u64 v[220:221], s[28:29], 0, v[152:153]
	global_load_lds_dwordx4 v[184:185], off
	v_lshl_add_u64 v[184:185], s[54:55], 0, v[158:159]
	s_add_i32 m0, s56, 0x2000
	v_lshl_add_u64 v[222:223], s[28:29], 0, v[156:157]
	global_load_lds_dwordx4 v[184:185], off
	s_mov_b32 m0, s40
	s_nop 0
	global_load_lds_dwordx4 v[220:221], off
	s_mov_b32 m0, s41
	s_nop 0
	global_load_lds_dwordx4 v[222:223], off
	ds_read_b128 v[184:187], v182 offset:16384
	ds_read_b128 v[188:191], v182 offset:17408
	ds_read_b128 v[192:195], v182 offset:18432
	ds_read_b128 v[196:199], v182 offset:19456
	ds_read_b128 v[200:203], v182 offset:20480
	ds_read_b128 v[204:207], v182 offset:21504
	ds_read_b128 v[208:211], v182 offset:22528
	ds_read_b128 v[212:215], v182 offset:23552
	s_waitcnt vmcnt(8)
	s_waitcnt lgkmcnt(0)
	s_barrier
	s_waitcnt lgkmcnt(0)
	v_mfma_f32_16x16x32_bf16 v[60:63], v[128:131], v[184:187], v[60:63]
	v_mfma_f32_16x16x32_bf16 v[60:63], v[132:135], v[188:191], v[60:63]
	v_mfma_f32_16x16x32_bf16 v[56:59], v[136:139], v[184:187], v[56:59]
	v_mfma_f32_16x16x32_bf16 v[56:59], v[140:143], v[188:191], v[56:59]
	v_mfma_f32_16x16x32_bf16 v[44:47], v[128:131], v[192:195], v[44:47]
	v_mfma_f32_16x16x32_bf16 v[44:47], v[132:135], v[196:199], v[44:47]
	v_mfma_f32_16x16x32_bf16 v[40:43], v[136:139], v[192:195], v[40:43]
	v_mfma_f32_16x16x32_bf16 v[40:43], v[140:143], v[196:199], v[40:43]
	v_mfma_f32_16x16x32_bf16 v[28:31], v[128:131], v[200:203], v[28:31]
	v_mfma_f32_16x16x32_bf16 v[28:31], v[132:135], v[204:207], v[28:31]
	v_mfma_f32_16x16x32_bf16 v[24:27], v[136:139], v[200:203], v[24:27]
	v_mfma_f32_16x16x32_bf16 v[24:27], v[140:143], v[204:207], v[24:27]
	v_mfma_f32_16x16x32_bf16 v[12:15], v[128:131], v[208:211], v[12:15]
	v_mfma_f32_16x16x32_bf16 v[12:15], v[132:135], v[212:215], v[12:15]
	v_mfma_f32_16x16x32_bf16 v[8:11], v[136:139], v[208:211], v[8:11]
	v_mfma_f32_16x16x32_bf16 v[8:11], v[140:143], v[212:215], v[8:11]
	v_mfma_f32_16x16x32_bf16 v[52:55], v[144:147], v[184:187], v[52:55]
	v_mfma_f32_16x16x32_bf16 v[52:55], v[148:151], v[188:191], v[52:55]
	v_mfma_f32_16x16x32_bf16 v[48:51], v[170:173], v[184:187], v[48:51]
	v_mfma_f32_16x16x32_bf16 v[48:51], v[174:177], v[188:191], v[48:51]
	v_mfma_f32_16x16x32_bf16 v[36:39], v[144:147], v[192:195], v[36:39]
	v_mfma_f32_16x16x32_bf16 v[36:39], v[148:151], v[196:199], v[36:39]
	v_mfma_f32_16x16x32_bf16 v[32:35], v[170:173], v[192:195], v[32:35]
	v_mfma_f32_16x16x32_bf16 v[32:35], v[174:177], v[196:199], v[32:35]
	v_mfma_f32_16x16x32_bf16 v[20:23], v[144:147], v[200:203], v[20:23]
	v_mfma_f32_16x16x32_bf16 v[20:23], v[148:151], v[204:207], v[20:23]
	v_mfma_f32_16x16x32_bf16 v[16:19], v[170:173], v[200:203], v[16:19]
	v_mfma_f32_16x16x32_bf16 v[16:19], v[174:177], v[204:207], v[16:19]
	v_mfma_f32_16x16x32_bf16 v[4:7], v[144:147], v[208:211], v[4:7]
	v_mfma_f32_16x16x32_bf16 v[4:7], v[148:151], v[212:215], v[4:7]
	v_mfma_f32_16x16x32_bf16 v[0:3], v[170:173], v[208:211], v[0:3]
	v_mfma_f32_16x16x32_bf16 v[0:3], v[174:177], v[212:215], v[0:3]
	s_barrier
	s_add_i32 s54, 0, 0x18000
	s_add_i32 s55, 0, 0x1c000
	v_add_u32_e32 v140, s54, v178
	v_add_u32_e32 v174, s55, v178
	ds_read_b128 v[128:131], v140
	ds_read_b128 v[132:135], v140 offset:1024
	ds_read_b128 v[136:139], v140 offset:2048
	ds_read_b128 v[140:143], v140 offset:3072
	ds_read_b128 v[144:147], v174
	ds_read_b128 v[148:151], v174 offset:1024
	ds_read_b128 v[170:173], v174 offset:2048
	ds_read_b128 v[174:177], v174 offset:3072
	s_add_u32 s28, s28, 0x40000
	s_addc_u32 s29, s29, 0
	s_mov_b32 m0, s42
	v_lshl_add_u64 v[184:185], s[28:29], 0, v[152:153]
	global_load_lds_dwordx4 v[184:185], off
	v_lshl_add_u64 v[184:185], s[28:29], 0, v[156:157]
	s_mov_b32 m0, s43
	s_nop 0
	global_load_lds_dwordx4 v[184:185], off
	ds_read_b128 v[184:187], v182 offset:32768
	ds_read_b128 v[188:191], v182 offset:33792
	ds_read_b128 v[192:195], v182 offset:34816
	ds_read_b128 v[196:199], v182 offset:35840
	ds_read_b128 v[200:203], v182 offset:36864
	ds_read_b128 v[204:207], v182 offset:37888
	ds_read_b128 v[208:211], v182 offset:38912
	ds_read_b128 v[212:215], v182 offset:39936
	s_waitcnt vmcnt(8)
	s_waitcnt lgkmcnt(0)
	s_barrier
	s_waitcnt lgkmcnt(0)
	v_mfma_f32_16x16x32_bf16 v[124:127], v[128:131], v[184:187], v[124:127]
	v_mfma_f32_16x16x32_bf16 v[124:127], v[132:135], v[188:191], v[124:127]
	v_mfma_f32_16x16x32_bf16 v[120:123], v[136:139], v[184:187], v[120:123]
	v_mfma_f32_16x16x32_bf16 v[120:123], v[140:143], v[188:191], v[120:123]
	v_mfma_f32_16x16x32_bf16 v[108:111], v[128:131], v[192:195], v[108:111]
	v_mfma_f32_16x16x32_bf16 v[108:111], v[132:135], v[196:199], v[108:111]
	v_mfma_f32_16x16x32_bf16 v[104:107], v[136:139], v[192:195], v[104:107]
	v_mfma_f32_16x16x32_bf16 v[104:107], v[140:143], v[196:199], v[104:107]
	v_mfma_f32_16x16x32_bf16 v[92:95], v[128:131], v[200:203], v[92:95]
	v_mfma_f32_16x16x32_bf16 v[92:95], v[132:135], v[204:207], v[92:95]
	v_mfma_f32_16x16x32_bf16 v[88:91], v[136:139], v[200:203], v[88:91]
	v_mfma_f32_16x16x32_bf16 v[88:91], v[140:143], v[204:207], v[88:91]
	v_mfma_f32_16x16x32_bf16 v[76:79], v[128:131], v[208:211], v[76:79]
	v_mfma_f32_16x16x32_bf16 v[76:79], v[132:135], v[212:215], v[76:79]
	v_mfma_f32_16x16x32_bf16 v[72:75], v[136:139], v[208:211], v[72:75]
	v_mfma_f32_16x16x32_bf16 v[72:75], v[140:143], v[212:215], v[72:75]
	v_mfma_f32_16x16x32_bf16 v[116:119], v[144:147], v[184:187], v[116:119]
	v_mfma_f32_16x16x32_bf16 v[116:119], v[148:151], v[188:191], v[116:119]
	v_mfma_f32_16x16x32_bf16 v[112:115], v[170:173], v[184:187], v[112:115]
	v_mfma_f32_16x16x32_bf16 v[112:115], v[174:177], v[188:191], v[112:115]
	v_mfma_f32_16x16x32_bf16 v[100:103], v[144:147], v[192:195], v[100:103]
	v_mfma_f32_16x16x32_bf16 v[100:103], v[148:151], v[196:199], v[100:103]
	v_mfma_f32_16x16x32_bf16 v[96:99], v[170:173], v[192:195], v[96:99]
	v_mfma_f32_16x16x32_bf16 v[96:99], v[174:177], v[196:199], v[96:99]
	v_mfma_f32_16x16x32_bf16 v[84:87], v[144:147], v[200:203], v[84:87]
	v_mfma_f32_16x16x32_bf16 v[84:87], v[148:151], v[204:207], v[84:87]
	v_mfma_f32_16x16x32_bf16 v[80:83], v[170:173], v[200:203], v[80:83]
	v_mfma_f32_16x16x32_bf16 v[80:83], v[174:177], v[204:207], v[80:83]
	v_mfma_f32_16x16x32_bf16 v[68:71], v[144:147], v[208:211], v[68:71]
	v_mfma_f32_16x16x32_bf16 v[68:71], v[148:151], v[212:215], v[68:71]
	v_mfma_f32_16x16x32_bf16 v[64:67], v[170:173], v[208:211], v[64:67]
	v_mfma_f32_16x16x32_bf16 v[64:67], v[174:177], v[212:215], v[64:67]
	s_barrier
	s_add_i32 s28, s54, s39
	v_lshl_add_u64 v[184:185], v[216:217], 0, s[14:15]
	s_mov_b32 m0, s28
	s_nop 0
	global_load_lds_dwordx4 v[184:185], off
	s_add_i32 m0, s28, 0x2000
	s_add_u32 s26, s26, 0x100080
	v_lshl_add_u64 v[184:185], v[218:219], 0, s[14:15]
	s_addc_u32 s27, s27, 0
	s_add_i32 s28, s55, s39
	global_load_lds_dwordx4 v[184:185], off
	v_lshl_add_u64 v[184:185], s[26:27], 0, v[154:155]
	s_mov_b32 m0, s28
	s_nop 0
	global_load_lds_dwordx4 v[184:185], off
	v_lshl_add_u64 v[184:185], s[26:27], 0, v[158:159]
	s_add_i32 m0, s28, 0x2000
	s_nop 0
	global_load_lds_dwordx4 v[184:185], off
	v_lshl_add_u64 v[184:185], v[220:221], 0, s[14:15]
	s_mov_b32 m0, s45
	s_nop 0
	global_load_lds_dwordx4 v[184:185], off
	v_lshl_add_u64 v[184:185], v[222:223], 0, s[14:15]
	s_mov_b32 m0, s46
	s_nop 0
	global_load_lds_dwordx4 v[184:185], off
	ds_read_b128 v[184:187], v182 offset:49152
	ds_read_b128 v[188:191], v182 offset:50176
	ds_read_b128 v[192:195], v182 offset:51200
	ds_read_b128 v[196:199], v182 offset:52224
	ds_read_b128 v[200:203], v182 offset:53248
	ds_read_b128 v[204:207], v182 offset:54272
	ds_read_b128 v[208:211], v182 offset:55296
	ds_read_b128 v[212:215], v182 offset:56320
	s_waitcnt vmcnt(8)
	s_waitcnt lgkmcnt(0)
	s_barrier
	s_waitcnt lgkmcnt(0)
	v_mfma_f32_16x16x32_bf16 v[60:63], v[128:131], v[184:187], v[60:63]
	v_mfma_f32_16x16x32_bf16 v[60:63], v[132:135], v[188:191], v[60:63]
	v_mfma_f32_16x16x32_bf16 v[56:59], v[136:139], v[184:187], v[56:59]
	v_mfma_f32_16x16x32_bf16 v[56:59], v[140:143], v[188:191], v[56:59]
	v_mfma_f32_16x16x32_bf16 v[44:47], v[128:131], v[192:195], v[44:47]
	v_mfma_f32_16x16x32_bf16 v[44:47], v[132:135], v[196:199], v[44:47]
	v_mfma_f32_16x16x32_bf16 v[40:43], v[136:139], v[192:195], v[40:43]
	v_mfma_f32_16x16x32_bf16 v[40:43], v[140:143], v[196:199], v[40:43]
	v_mfma_f32_16x16x32_bf16 v[28:31], v[128:131], v[200:203], v[28:31]
	v_mfma_f32_16x16x32_bf16 v[28:31], v[132:135], v[204:207], v[28:31]
	v_mfma_f32_16x16x32_bf16 v[24:27], v[136:139], v[200:203], v[24:27]
	v_mfma_f32_16x16x32_bf16 v[24:27], v[140:143], v[204:207], v[24:27]
	v_mfma_f32_16x16x32_bf16 v[12:15], v[128:131], v[208:211], v[12:15]
	v_mfma_f32_16x16x32_bf16 v[12:15], v[132:135], v[212:215], v[12:15]
	v_mfma_f32_16x16x32_bf16 v[8:11], v[136:139], v[208:211], v[8:11]
	v_mfma_f32_16x16x32_bf16 v[8:11], v[140:143], v[212:215], v[8:11]
	v_mfma_f32_16x16x32_bf16 v[52:55], v[144:147], v[184:187], v[52:55]
	v_mfma_f32_16x16x32_bf16 v[52:55], v[148:151], v[188:191], v[52:55]
	v_mfma_f32_16x16x32_bf16 v[48:51], v[170:173], v[184:187], v[48:51]
	v_mfma_f32_16x16x32_bf16 v[48:51], v[174:177], v[188:191], v[48:51]
	v_mfma_f32_16x16x32_bf16 v[36:39], v[144:147], v[192:195], v[36:39]
	v_mfma_f32_16x16x32_bf16 v[36:39], v[148:151], v[196:199], v[36:39]
	v_mfma_f32_16x16x32_bf16 v[32:35], v[170:173], v[192:195], v[32:35]
	v_mfma_f32_16x16x32_bf16 v[32:35], v[174:177], v[196:199], v[32:35]
	v_mfma_f32_16x16x32_bf16 v[20:23], v[144:147], v[200:203], v[20:23]
	v_mfma_f32_16x16x32_bf16 v[20:23], v[148:151], v[204:207], v[20:23]
	v_mfma_f32_16x16x32_bf16 v[16:19], v[170:173], v[200:203], v[16:19]
	v_mfma_f32_16x16x32_bf16 v[16:19], v[174:177], v[204:207], v[16:19]
	v_mfma_f32_16x16x32_bf16 v[4:7], v[144:147], v[208:211], v[4:7]
	v_mfma_f32_16x16x32_bf16 v[4:7], v[148:151], v[212:215], v[4:7]
	v_mfma_f32_16x16x32_bf16 v[0:3], v[170:173], v[208:211], v[0:3]
	v_mfma_f32_16x16x32_bf16 v[0:3], v[174:177], v[212:215], v[0:3]
	s_barrier
	s_add_i32 s35, s35, 2
	s_add_u32 s24, s24, 0x100
	s_addc_u32 s25, s25, 0
	s_add_u32 s31, s31, 0x100
	s_addc_u32 s34, s34, 0
	s_cmp_gt_u32 s35, 13
	s_cbranch_scc0 .LBB0_1435
	s_and_b64 vcc, exec, s[8:9]
	s_cbranch_vccz .LBB0_1438
	s_barrier

.LBB0_1543:
	ds_read_b128 v[128:131], v167
	ds_read_b128 v[154:157], v167 offset:1024
	ds_read_b128 v[172:175], v167 offset:2048
	ds_read_b128 v[176:179], v167 offset:3072
	ds_read_b128 v[180:183], v168
	ds_read_b128 v[184:187], v168 offset:1024
	ds_read_b128 v[188:191], v168 offset:2048
	ds_read_b128 v[192:195], v168 offset:3072
	s_add_u32 s22, s20, 0x1000
	s_addc_u32 s23, s21, 0
	s_cmp_eq_u32 s54, 60
	s_cselect_b32 s27, s13, s23
	s_cselect_b32 s26, s50, s22
	s_cselect_b32 s25, s11, s53
	s_cselect_b32 s24, s51, s52
	v_lshl_add_u64 v[160:161], s[20:21], 0, v[144:145]
	s_add_i32 m0, s19, 0xc000
	s_nop 0
	global_load_lds_dwordx4 v[160:161], off
	v_lshl_add_u64 v[160:161], s[20:21], 0, v[146:147]
	s_add_i32 m0, s19, 0xe000
	s_nop 0
	global_load_lds_dwordx4 v[160:161], off
	ds_read_b128 v[196:199], v169
	ds_read_b128 v[200:203], v169 offset:1024
	ds_read_b128 v[204:207], v169 offset:2048
	ds_read_b128 v[208:211], v169 offset:3072
	ds_read_b128 v[212:215], v169 offset:4096
	ds_read_b128 v[216:219], v169 offset:5120
	ds_read_b128 v[220:223], v169 offset:6144
	ds_read_b128 v[224:227], v169 offset:7168
	s_waitcnt vmcnt(8)
	s_waitcnt lgkmcnt(0)
	s_barrier
	s_waitcnt lgkmcnt(0)
	v_mfma_f32_16x16x32_bf16 v[124:127], v[128:131], v[196:199], v[124:127]
	v_mfma_f32_16x16x32_bf16 v[124:127], v[154:157], v[200:203], v[124:127]
	v_mfma_f32_16x16x32_bf16 v[120:123], v[172:175], v[196:199], v[120:123]
	v_mfma_f32_16x16x32_bf16 v[120:123], v[176:179], v[200:203], v[120:123]
	v_mfma_f32_16x16x32_bf16 v[108:111], v[128:131], v[204:207], v[108:111]
	v_mfma_f32_16x16x32_bf16 v[108:111], v[154:157], v[208:211], v[108:111]
	v_mfma_f32_16x16x32_bf16 v[104:107], v[172:175], v[204:207], v[104:107]
	v_mfma_f32_16x16x32_bf16 v[104:107], v[176:179], v[208:211], v[104:107]
	v_mfma_f32_16x16x32_bf16 v[92:95], v[128:131], v[212:215], v[92:95]
	v_mfma_f32_16x16x32_bf16 v[92:95], v[154:157], v[216:219], v[92:95]
	v_mfma_f32_16x16x32_bf16 v[88:91], v[172:175], v[212:215], v[88:91]
	v_mfma_f32_16x16x32_bf16 v[88:91], v[176:179], v[216:219], v[88:91]
	v_mfma_f32_16x16x32_bf16 v[76:79], v[128:131], v[220:223], v[76:79]
	v_mfma_f32_16x16x32_bf16 v[76:79], v[154:157], v[224:227], v[76:79]
	v_mfma_f32_16x16x32_bf16 v[72:75], v[172:175], v[220:223], v[72:75]
	v_mfma_f32_16x16x32_bf16 v[72:75], v[176:179], v[224:227], v[72:75]
	v_mfma_f32_16x16x32_bf16 v[116:119], v[180:183], v[196:199], v[116:119]
	v_mfma_f32_16x16x32_bf16 v[116:119], v[184:187], v[200:203], v[116:119]
	v_mfma_f32_16x16x32_bf16 v[112:115], v[188:191], v[196:199], v[112:115]
	v_mfma_f32_16x16x32_bf16 v[112:115], v[192:195], v[200:203], v[112:115]
	v_mfma_f32_16x16x32_bf16 v[100:103], v[180:183], v[204:207], v[100:103]
	v_mfma_f32_16x16x32_bf16 v[100:103], v[184:187], v[208:211], v[100:103]
	v_mfma_f32_16x16x32_bf16 v[96:99], v[188:191], v[204:207], v[96:99]
	v_mfma_f32_16x16x32_bf16 v[96:99], v[192:195], v[208:211], v[96:99]
	v_mfma_f32_16x16x32_bf16 v[84:87], v[180:183], v[212:215], v[84:87]
	v_mfma_f32_16x16x32_bf16 v[84:87], v[184:187], v[216:219], v[84:87]
	v_mfma_f32_16x16x32_bf16 v[80:83], v[188:191], v[212:215], v[80:83]
	v_mfma_f32_16x16x32_bf16 v[80:83], v[192:195], v[216:219], v[80:83]
	v_mfma_f32_16x16x32_bf16 v[68:71], v[180:183], v[220:223], v[68:71]
	v_mfma_f32_16x16x32_bf16 v[68:71], v[184:187], v[224:227], v[68:71]
	v_mfma_f32_16x16x32_bf16 v[64:67], v[188:191], v[220:223], v[64:67]
	v_mfma_f32_16x16x32_bf16 v[64:67], v[192:195], v[224:227], v[64:67]
	s_barrier
	s_add_i32 s20, s45, s30
	v_lshl_add_u64 v[160:161], s[24:25], 0, v[134:135]
	s_mov_b32 m0, s20
	v_lshl_add_u64 v[164:165], s[24:25], 0, v[138:139]
	global_load_lds_dwordx4 v[160:161], off
	s_add_i32 m0, s20, 0x2000
	s_add_u32 s20, s24, 0x100000
	s_addc_u32 s21, s25, 0
	s_add_i32 s55, s46, s30
	global_load_lds_dwordx4 v[164:165], off
	v_lshl_add_u64 v[196:197], s[20:21], 0, v[134:135]
	s_mov_b32 m0, s55
	v_lshl_add_u64 v[228:229], s[26:27], 0, v[132:133]
	global_load_lds_dwordx4 v[196:197], off
	v_lshl_add_u64 v[196:197], s[20:21], 0, v[138:139]
	s_add_i32 m0, s55, 0x2000
	v_lshl_add_u64 v[230:231], s[26:27], 0, v[136:137]
	global_load_lds_dwordx4 v[196:197], off
	s_mov_b32 m0, s19
	s_nop 0
	global_load_lds_dwordx4 v[228:229], off
	s_mov_b32 m0, s36
	s_nop 0
	global_load_lds_dwordx4 v[230:231], off
	ds_read_b128 v[196:199], v169 offset:16384
	ds_read_b128 v[200:203], v169 offset:17408
	ds_read_b128 v[204:207], v169 offset:18432
	ds_read_b128 v[208:211], v169 offset:19456
	ds_read_b128 v[212:215], v169 offset:20480
	ds_read_b128 v[216:219], v169 offset:21504
	ds_read_b128 v[220:223], v169 offset:22528
	ds_read_b128 v[224:227], v169 offset:23552
	s_waitcnt vmcnt(8)
	s_waitcnt lgkmcnt(0)
	s_barrier
	s_waitcnt lgkmcnt(0)
	v_mfma_f32_16x16x32_bf16 v[60:63], v[128:131], v[196:199], v[60:63]
	v_mfma_f32_16x16x32_bf16 v[60:63], v[154:157], v[200:203], v[60:63]
	v_mfma_f32_16x16x32_bf16 v[56:59], v[172:175], v[196:199], v[56:59]
	v_mfma_f32_16x16x32_bf16 v[56:59], v[176:179], v[200:203], v[56:59]
	v_mfma_f32_16x16x32_bf16 v[44:47], v[128:131], v[204:207], v[44:47]
	v_mfma_f32_16x16x32_bf16 v[44:47], v[154:157], v[208:211], v[44:47]
	v_mfma_f32_16x16x32_bf16 v[40:43], v[172:175], v[204:207], v[40:43]
	v_mfma_f32_16x16x32_bf16 v[40:43], v[176:179], v[208:211], v[40:43]
	v_mfma_f32_16x16x32_bf16 v[28:31], v[128:131], v[212:215], v[28:31]
	v_mfma_f32_16x16x32_bf16 v[28:31], v[154:157], v[216:219], v[28:31]
	v_mfma_f32_16x16x32_bf16 v[24:27], v[172:175], v[212:215], v[24:27]
	v_mfma_f32_16x16x32_bf16 v[24:27], v[176:179], v[216:219], v[24:27]
	v_mfma_f32_16x16x32_bf16 v[12:15], v[128:131], v[220:223], v[12:15]
	v_mfma_f32_16x16x32_bf16 v[12:15], v[154:157], v[224:227], v[12:15]
	v_mfma_f32_16x16x32_bf16 v[8:11], v[172:175], v[220:223], v[8:11]
	v_mfma_f32_16x16x32_bf16 v[8:11], v[176:179], v[224:227], v[8:11]
	v_mfma_f32_16x16x32_bf16 v[52:55], v[180:183], v[196:199], v[52:55]
	v_mfma_f32_16x16x32_bf16 v[52:55], v[184:187], v[200:203], v[52:55]
	v_mfma_f32_16x16x32_bf16 v[48:51], v[188:191], v[196:199], v[48:51]
	v_mfma_f32_16x16x32_bf16 v[48:51], v[192:195], v[200:203], v[48:51]
	v_mfma_f32_16x16x32_bf16 v[36:39], v[180:183], v[204:207], v[36:39]
	v_mfma_f32_16x16x32_bf16 v[36:39], v[184:187], v[208:211], v[36:39]
	v_mfma_f32_16x16x32_bf16 v[32:35], v[188:191], v[204:207], v[32:35]
	v_mfma_f32_16x16x32_bf16 v[32:35], v[192:195], v[208:211], v[32:35]
	v_mfma_f32_16x16x32_bf16 v[20:23], v[180:183], v[212:215], v[20:23]
	v_mfma_f32_16x16x32_bf16 v[20:23], v[184:187], v[216:219], v[20:23]
	v_mfma_f32_16x16x32_bf16 v[16:19], v[188:191], v[212:215], v[16:19]
	v_mfma_f32_16x16x32_bf16 v[16:19], v[192:195], v[216:219], v[16:19]
	v_mfma_f32_16x16x32_bf16 v[4:7], v[180:183], v[220:223], v[4:7]
	v_mfma_f32_16x16x32_bf16 v[4:7], v[184:187], v[224:227], v[4:7]
	v_mfma_f32_16x16x32_bf16 v[0:3], v[188:191], v[220:223], v[0:3]
	v_mfma_f32_16x16x32_bf16 v[0:3], v[192:195], v[224:227], v[0:3]
	s_barrier
	s_add_i32 s55, 0, 0x18000
	v_add_u32_e32 v153, s55, v159
	s_add_i32 s56, 0, 0x1c000
	ds_read_b128 v[128:131], v153
	ds_read_b128 v[154:157], v153 offset:1024
	ds_read_b128 v[172:175], v153 offset:2048
	ds_read_b128 v[176:179], v153 offset:3072
	v_add_u32_e32 v153, s56, v159
	ds_read_b128 v[180:183], v153
	ds_read_b128 v[184:187], v153 offset:1024
	ds_read_b128 v[188:191], v153 offset:2048
	ds_read_b128 v[192:195], v153 offset:3072
	s_add_u32 s20, s26, 0x100000
	s_addc_u32 s21, s27, 0
	s_mov_b32 m0, s37
	v_lshl_add_u64 v[196:197], s[20:21], 0, v[132:133]
	global_load_lds_dwordx4 v[196:197], off
	v_lshl_add_u64 v[196:197], s[20:21], 0, v[136:137]
	s_mov_b32 m0, s38
	s_nop 0
	global_load_lds_dwordx4 v[196:197], off
	ds_read_b128 v[196:199], v169 offset:32768
	ds_read_b128 v[200:203], v169 offset:33792
	ds_read_b128 v[204:207], v169 offset:34816
	ds_read_b128 v[208:211], v169 offset:35840
	ds_read_b128 v[212:215], v169 offset:36864
	ds_read_b128 v[216:219], v169 offset:37888
	ds_read_b128 v[220:223], v169 offset:38912
	ds_read_b128 v[224:227], v169 offset:39936
	s_waitcnt vmcnt(8)
	s_waitcnt lgkmcnt(0)
	s_barrier
	s_waitcnt lgkmcnt(0)
	v_mfma_f32_16x16x32_bf16 v[124:127], v[128:131], v[196:199], v[124:127]
	v_mfma_f32_16x16x32_bf16 v[124:127], v[154:157], v[200:203], v[124:127]
	v_mfma_f32_16x16x32_bf16 v[120:123], v[172:175], v[196:199], v[120:123]
	v_mfma_f32_16x16x32_bf16 v[120:123], v[176:179], v[200:203], v[120:123]
	v_mfma_f32_16x16x32_bf16 v[108:111], v[128:131], v[204:207], v[108:111]
	v_mfma_f32_16x16x32_bf16 v[108:111], v[154:157], v[208:211], v[108:111]
	v_mfma_f32_16x16x32_bf16 v[104:107], v[172:175], v[204:207], v[104:107]
	v_mfma_f32_16x16x32_bf16 v[104:107], v[176:179], v[208:211], v[104:107]
	v_mfma_f32_16x16x32_bf16 v[92:95], v[128:131], v[212:215], v[92:95]
	v_mfma_f32_16x16x32_bf16 v[92:95], v[154:157], v[216:219], v[92:95]
	v_mfma_f32_16x16x32_bf16 v[88:91], v[172:175], v[212:215], v[88:91]
	v_mfma_f32_16x16x32_bf16 v[88:91], v[176:179], v[216:219], v[88:91]
	v_mfma_f32_16x16x32_bf16 v[76:79], v[128:131], v[220:223], v[76:79]
	v_mfma_f32_16x16x32_bf16 v[76:79], v[154:157], v[224:227], v[76:79]
	v_mfma_f32_16x16x32_bf16 v[72:75], v[172:175], v[220:223], v[72:75]
	v_mfma_f32_16x16x32_bf16 v[72:75], v[176:179], v[224:227], v[72:75]
	v_mfma_f32_16x16x32_bf16 v[116:119], v[180:183], v[196:199], v[116:119]
	v_mfma_f32_16x16x32_bf16 v[116:119], v[184:187], v[200:203], v[116:119]
	v_mfma_f32_16x16x32_bf16 v[112:115], v[188:191], v[196:199], v[112:115]
	v_mfma_f32_16x16x32_bf16 v[112:115], v[192:195], v[200:203], v[112:115]
	v_mfma_f32_16x16x32_bf16 v[100:103], v[180:183], v[204:207], v[100:103]
	v_mfma_f32_16x16x32_bf16 v[100:103], v[184:187], v[208:211], v[100:103]
	v_mfma_f32_16x16x32_bf16 v[96:99], v[188:191], v[204:207], v[96:99]
	v_mfma_f32_16x16x32_bf16 v[96:99], v[192:195], v[208:211], v[96:99]
	v_mfma_f32_16x16x32_bf16 v[84:87], v[180:183], v[212:215], v[84:87]
	v_mfma_f32_16x16x32_bf16 v[84:87], v[184:187], v[216:219], v[84:87]
	v_mfma_f32_16x16x32_bf16 v[80:83], v[188:191], v[212:215], v[80:83]
	v_mfma_f32_16x16x32_bf16 v[80:83], v[192:195], v[216:219], v[80:83]
	v_mfma_f32_16x16x32_bf16 v[68:71], v[180:183], v[220:223], v[68:71]
	v_mfma_f32_16x16x32_bf16 v[68:71], v[184:187], v[224:227], v[68:71]
	v_mfma_f32_16x16x32_bf16 v[64:67], v[188:191], v[220:223], v[64:67]
	v_mfma_f32_16x16x32_bf16 v[64:67], v[192:195], v[224:227], v[64:67]
	s_barrier
	s_add_i32 s20, s55, s30
	v_lshl_add_u64 v[160:161], v[160:161], 0, s[8:9]
	s_mov_b32 m0, s20
	s_nop 0
	global_load_lds_dwordx4 v[160:161], off
	s_add_i32 m0, s20, 0x2000
	s_add_u32 s20, s24, 0x100800
	v_lshl_add_u64 v[160:161], v[164:165], 0, s[8:9]
	s_addc_u32 s21, s25, 0
	s_add_i32 s24, s56, s30
	global_load_lds_dwordx4 v[160:161], off
	v_lshl_add_u64 v[160:161], s[20:21], 0, v[134:135]
	s_mov_b32 m0, s24
	s_nop 0
	global_load_lds_dwordx4 v[160:161], off
	v_lshl_add_u64 v[160:161], s[20:21], 0, v[138:139]
	s_add_i32 m0, s24, 0x2000
	s_nop 0
	global_load_lds_dwordx4 v[160:161], off
	v_lshl_add_u64 v[160:161], v[228:229], 0, s[8:9]
	s_mov_b32 m0, s41
	s_nop 0
	global_load_lds_dwordx4 v[160:161], off
	v_lshl_add_u64 v[160:161], v[230:231], 0, s[8:9]
	s_mov_b32 m0, s42
	s_nop 0
	global_load_lds_dwordx4 v[160:161], off
	ds_read_b128 v[196:199], v169 offset:49152
	ds_read_b128 v[200:203], v169 offset:50176
	ds_read_b128 v[204:207], v169 offset:51200
	ds_read_b128 v[208:211], v169 offset:52224
	ds_read_b128 v[212:215], v169 offset:53248
	ds_read_b128 v[216:219], v169 offset:54272
	ds_read_b128 v[220:223], v169 offset:55296
	ds_read_b128 v[224:227], v169 offset:56320
	s_waitcnt vmcnt(8)
	s_waitcnt lgkmcnt(0)
	s_barrier
	s_waitcnt lgkmcnt(0)
	v_mfma_f32_16x16x32_bf16 v[60:63], v[128:131], v[196:199], v[60:63]
	v_mfma_f32_16x16x32_bf16 v[60:63], v[154:157], v[200:203], v[60:63]
	v_mfma_f32_16x16x32_bf16 v[56:59], v[172:175], v[196:199], v[56:59]
	v_mfma_f32_16x16x32_bf16 v[56:59], v[176:179], v[200:203], v[56:59]
	v_mfma_f32_16x16x32_bf16 v[44:47], v[128:131], v[204:207], v[44:47]
	v_mfma_f32_16x16x32_bf16 v[44:47], v[154:157], v[208:211], v[44:47]
	v_mfma_f32_16x16x32_bf16 v[40:43], v[172:175], v[204:207], v[40:43]
	v_mfma_f32_16x16x32_bf16 v[40:43], v[176:179], v[208:211], v[40:43]
	v_mfma_f32_16x16x32_bf16 v[28:31], v[128:131], v[212:215], v[28:31]
	v_mfma_f32_16x16x32_bf16 v[28:31], v[154:157], v[216:219], v[28:31]
	v_mfma_f32_16x16x32_bf16 v[24:27], v[172:175], v[212:215], v[24:27]
	v_mfma_f32_16x16x32_bf16 v[24:27], v[176:179], v[216:219], v[24:27]
	v_mfma_f32_16x16x32_bf16 v[12:15], v[128:131], v[220:223], v[12:15]
	v_mfma_f32_16x16x32_bf16 v[12:15], v[154:157], v[224:227], v[12:15]
	v_mfma_f32_16x16x32_bf16 v[8:11], v[172:175], v[220:223], v[8:11]
	v_mfma_f32_16x16x32_bf16 v[8:11], v[176:179], v[224:227], v[8:11]
	v_mfma_f32_16x16x32_bf16 v[52:55], v[180:183], v[196:199], v[52:55]
	v_mfma_f32_16x16x32_bf16 v[52:55], v[184:187], v[200:203], v[52:55]
	v_mfma_f32_16x16x32_bf16 v[48:51], v[188:191], v[196:199], v[48:51]
	v_mfma_f32_16x16x32_bf16 v[48:51], v[192:195], v[200:203], v[48:51]
	v_mfma_f32_16x16x32_bf16 v[36:39], v[180:183], v[204:207], v[36:39]
	v_mfma_f32_16x16x32_bf16 v[36:39], v[184:187], v[208:211], v[36:39]
	v_mfma_f32_16x16x32_bf16 v[32:35], v[188:191], v[204:207], v[32:35]
	v_mfma_f32_16x16x32_bf16 v[32:35], v[192:195], v[208:211], v[32:35]
	v_mfma_f32_16x16x32_bf16 v[20:23], v[180:183], v[212:215], v[20:23]
	v_mfma_f32_16x16x32_bf16 v[20:23], v[184:187], v[216:219], v[20:23]
	v_mfma_f32_16x16x32_bf16 v[16:19], v[188:191], v[212:215], v[16:19]
	v_mfma_f32_16x16x32_bf16 v[16:19], v[192:195], v[216:219], v[16:19]
	v_mfma_f32_16x16x32_bf16 v[4:7], v[180:183], v[220:223], v[4:7]
	v_mfma_f32_16x16x32_bf16 v[4:7], v[184:187], v[224:227], v[4:7]
	v_mfma_f32_16x16x32_bf16 v[0:3], v[188:191], v[220:223], v[0:3]
	v_mfma_f32_16x16x32_bf16 v[0:3], v[192:195], v[224:227], v[0:3]
	s_barrier
	s_add_i32 s54, s54, 2
	s_add_u32 s52, s52, 0x1000
	s_addc_u32 s53, s53, 0
	s_cmp_gt_u32 s54, 61
	s_mov_b64 s[20:21], s[22:23]
	s_cbranch_scc0 .LBB0_1543
	s_and_b64 vcc, exec, s[4:5]
	s_cbranch_vccz .LBB0_1546
	s_barrier

.LBB0_1625:
	ds_read_b128 v[128:131], v177
	ds_read_b128 v[132:135], v177 offset:1024
	ds_read_b128 v[136:139], v177 offset:2048
	ds_read_b128 v[140:143], v177 offset:3072
	ds_read_b128 v[144:147], v178
	ds_read_b128 v[148:151], v178 offset:1024
	ds_read_b128 v[170:173], v178 offset:2048
	ds_read_b128 v[182:185], v178 offset:3072
	s_add_u32 s24, s22, 0xffc00800
	s_addc_u32 s25, s23, -1
	s_cmpk_eq_i32 s57, 0xfc
	s_cselect_b32 s27, s29, s25
	s_cselect_b32 s26, s53, s24
	s_cselect_b32 s25, s17, s56
	s_cselect_b32 s24, s54, s55
	v_lshl_add_u64 v[186:187], s[22:23], 0, v[162:163]
	s_add_i32 m0, s38, 0xc000
	s_nop 0
	global_load_lds_dwordx4 v[186:187], off
	v_lshl_add_u64 v[186:187], s[22:23], 0, v[164:165]
	s_add_i32 m0, s38, 0xe000
	s_nop 0
	global_load_lds_dwordx4 v[186:187], off
	ds_read_b128 v[186:189], v179
	ds_read_b128 v[190:193], v179 offset:1024
	ds_read_b128 v[194:197], v179 offset:2048
	ds_read_b128 v[198:201], v179 offset:3072
	ds_read_b128 v[202:205], v179 offset:4096
	ds_read_b128 v[206:209], v179 offset:5120
	ds_read_b128 v[210:213], v179 offset:6144
	ds_read_b128 v[214:217], v179 offset:7168
	s_waitcnt vmcnt(8)
	s_waitcnt lgkmcnt(0)
	s_barrier
	s_waitcnt lgkmcnt(0)
	v_mfma_f32_16x16x32_bf16 v[124:127], v[128:131], v[186:189], v[124:127]
	v_mfma_f32_16x16x32_bf16 v[124:127], v[132:135], v[190:193], v[124:127]
	v_mfma_f32_16x16x32_bf16 v[120:123], v[136:139], v[186:189], v[120:123]
	v_mfma_f32_16x16x32_bf16 v[120:123], v[140:143], v[190:193], v[120:123]
	v_mfma_f32_16x16x32_bf16 v[108:111], v[128:131], v[194:197], v[108:111]
	v_mfma_f32_16x16x32_bf16 v[108:111], v[132:135], v[198:201], v[108:111]
	v_mfma_f32_16x16x32_bf16 v[104:107], v[136:139], v[194:197], v[104:107]
	v_mfma_f32_16x16x32_bf16 v[104:107], v[140:143], v[198:201], v[104:107]
	v_mfma_f32_16x16x32_bf16 v[92:95], v[128:131], v[202:205], v[92:95]
	v_mfma_f32_16x16x32_bf16 v[92:95], v[132:135], v[206:209], v[92:95]
	v_mfma_f32_16x16x32_bf16 v[88:91], v[136:139], v[202:205], v[88:91]
	v_mfma_f32_16x16x32_bf16 v[88:91], v[140:143], v[206:209], v[88:91]
	v_mfma_f32_16x16x32_bf16 v[76:79], v[128:131], v[210:213], v[76:79]
	v_mfma_f32_16x16x32_bf16 v[76:79], v[132:135], v[214:217], v[76:79]
	v_mfma_f32_16x16x32_bf16 v[72:75], v[136:139], v[210:213], v[72:75]
	v_mfma_f32_16x16x32_bf16 v[72:75], v[140:143], v[214:217], v[72:75]
	v_mfma_f32_16x16x32_bf16 v[116:119], v[144:147], v[186:189], v[116:119]
	v_mfma_f32_16x16x32_bf16 v[116:119], v[148:151], v[190:193], v[116:119]
	v_mfma_f32_16x16x32_bf16 v[112:115], v[170:173], v[186:189], v[112:115]
	v_mfma_f32_16x16x32_bf16 v[112:115], v[182:185], v[190:193], v[112:115]
	v_mfma_f32_16x16x32_bf16 v[100:103], v[144:147], v[194:197], v[100:103]
	v_mfma_f32_16x16x32_bf16 v[100:103], v[148:151], v[198:201], v[100:103]
	v_mfma_f32_16x16x32_bf16 v[96:99], v[170:173], v[194:197], v[96:99]
	v_mfma_f32_16x16x32_bf16 v[96:99], v[182:185], v[198:201], v[96:99]
	v_mfma_f32_16x16x32_bf16 v[84:87], v[144:147], v[202:205], v[84:87]
	v_mfma_f32_16x16x32_bf16 v[84:87], v[148:151], v[206:209], v[84:87]
	v_mfma_f32_16x16x32_bf16 v[80:83], v[170:173], v[202:205], v[80:83]
	v_mfma_f32_16x16x32_bf16 v[80:83], v[182:185], v[206:209], v[80:83]
	v_mfma_f32_16x16x32_bf16 v[68:71], v[144:147], v[210:213], v[68:71]
	v_mfma_f32_16x16x32_bf16 v[68:71], v[148:151], v[214:217], v[68:71]
	v_mfma_f32_16x16x32_bf16 v[64:67], v[170:173], v[210:213], v[64:67]
	v_mfma_f32_16x16x32_bf16 v[64:67], v[182:185], v[214:217], v[64:67]
	s_barrier
	s_add_i32 s58, s48, s37
	v_lshl_add_u64 v[218:219], s[24:25], 0, v[154:155]
	s_mov_b32 m0, s58
	v_lshl_add_u64 v[220:221], s[24:25], 0, v[158:159]
	global_load_lds_dwordx4 v[218:219], off
	s_add_i32 m0, s58, 0x2000
	s_add_u32 s58, s24, 0x400000
	s_addc_u32 s59, s25, 0
	s_add_i32 s60, s49, s37
	global_load_lds_dwordx4 v[220:221], off
	v_lshl_add_u64 v[186:187], s[58:59], 0, v[154:155]
	s_mov_b32 m0, s60
	v_lshl_add_u64 v[222:223], s[26:27], 0, v[152:153]
	global_load_lds_dwordx4 v[186:187], off
	v_lshl_add_u64 v[186:187], s[58:59], 0, v[158:159]
	s_add_i32 m0, s60, 0x2000
	v_lshl_add_u64 v[224:225], s[26:27], 0, v[156:157]
	global_load_lds_dwordx4 v[186:187], off
	s_mov_b32 m0, s38
	s_nop 0
	global_load_lds_dwordx4 v[222:223], off
	s_mov_b32 m0, s39
	s_nop 0
	global_load_lds_dwordx4 v[224:225], off
	ds_read_b128 v[186:189], v179 offset:16384
	ds_read_b128 v[190:193], v179 offset:17408
	ds_read_b128 v[194:197], v179 offset:18432
	ds_read_b128 v[198:201], v179 offset:19456
	ds_read_b128 v[202:205], v179 offset:20480
	ds_read_b128 v[206:209], v179 offset:21504
	ds_read_b128 v[210:213], v179 offset:22528
	ds_read_b128 v[214:217], v179 offset:23552
	s_waitcnt vmcnt(8)
	s_waitcnt lgkmcnt(0)
	s_barrier
	s_waitcnt lgkmcnt(0)
	v_mfma_f32_16x16x32_bf16 v[60:63], v[128:131], v[186:189], v[60:63]
	v_mfma_f32_16x16x32_bf16 v[60:63], v[132:135], v[190:193], v[60:63]
	v_mfma_f32_16x16x32_bf16 v[56:59], v[136:139], v[186:189], v[56:59]
	v_mfma_f32_16x16x32_bf16 v[56:59], v[140:143], v[190:193], v[56:59]
	v_mfma_f32_16x16x32_bf16 v[44:47], v[128:131], v[194:197], v[44:47]
	v_mfma_f32_16x16x32_bf16 v[44:47], v[132:135], v[198:201], v[44:47]
	v_mfma_f32_16x16x32_bf16 v[40:43], v[136:139], v[194:197], v[40:43]
	v_mfma_f32_16x16x32_bf16 v[40:43], v[140:143], v[198:201], v[40:43]
	v_mfma_f32_16x16x32_bf16 v[28:31], v[128:131], v[202:205], v[28:31]
	v_mfma_f32_16x16x32_bf16 v[28:31], v[132:135], v[206:209], v[28:31]
	v_mfma_f32_16x16x32_bf16 v[24:27], v[136:139], v[202:205], v[24:27]
	v_mfma_f32_16x16x32_bf16 v[24:27], v[140:143], v[206:209], v[24:27]
	v_mfma_f32_16x16x32_bf16 v[12:15], v[128:131], v[210:213], v[12:15]
	v_mfma_f32_16x16x32_bf16 v[12:15], v[132:135], v[214:217], v[12:15]
	v_mfma_f32_16x16x32_bf16 v[8:11], v[136:139], v[210:213], v[8:11]
	v_mfma_f32_16x16x32_bf16 v[8:11], v[140:143], v[214:217], v[8:11]
	v_mfma_f32_16x16x32_bf16 v[52:55], v[144:147], v[186:189], v[52:55]
	v_mfma_f32_16x16x32_bf16 v[52:55], v[148:151], v[190:193], v[52:55]
	v_mfma_f32_16x16x32_bf16 v[48:51], v[170:173], v[186:189], v[48:51]
	v_mfma_f32_16x16x32_bf16 v[48:51], v[182:185], v[190:193], v[48:51]
	v_mfma_f32_16x16x32_bf16 v[36:39], v[144:147], v[194:197], v[36:39]
	v_mfma_f32_16x16x32_bf16 v[36:39], v[148:151], v[198:201], v[36:39]
	v_mfma_f32_16x16x32_bf16 v[32:35], v[170:173], v[194:197], v[32:35]
	v_mfma_f32_16x16x32_bf16 v[32:35], v[182:185], v[198:201], v[32:35]
	v_mfma_f32_16x16x32_bf16 v[20:23], v[144:147], v[202:205], v[20:23]
	v_mfma_f32_16x16x32_bf16 v[20:23], v[148:151], v[206:209], v[20:23]
	v_mfma_f32_16x16x32_bf16 v[16:19], v[170:173], v[202:205], v[16:19]
	v_mfma_f32_16x16x32_bf16 v[16:19], v[182:185], v[206:209], v[16:19]
	v_mfma_f32_16x16x32_bf16 v[4:7], v[144:147], v[210:213], v[4:7]
	v_mfma_f32_16x16x32_bf16 v[4:7], v[148:151], v[214:217], v[4:7]
	v_mfma_f32_16x16x32_bf16 v[0:3], v[170:173], v[210:213], v[0:3]
	v_mfma_f32_16x16x32_bf16 v[0:3], v[182:185], v[214:217], v[0:3]
	s_barrier
	s_add_i32 s58, 0, 0x18000
	s_add_i32 s59, 0, 0x1c000
	v_add_u32_e32 v140, s58, v174
	v_add_u32_e32 v181, s59, v174
	ds_read_b128 v[128:131], v140
	ds_read_b128 v[132:135], v140 offset:1024
	ds_read_b128 v[136:139], v140 offset:2048
	ds_read_b128 v[140:143], v140 offset:3072
	ds_read_b128 v[144:147], v181
	ds_read_b128 v[148:151], v181 offset:1024
	ds_read_b128 v[170:173], v181 offset:2048
	ds_read_b128 v[182:185], v181 offset:3072
	s_add_u32 s26, s26, 0x400000
	s_addc_u32 s27, s27, 0
	s_mov_b32 m0, s40
	v_lshl_add_u64 v[186:187], s[26:27], 0, v[152:153]
	global_load_lds_dwordx4 v[186:187], off
	v_lshl_add_u64 v[186:187], s[26:27], 0, v[156:157]
	s_mov_b32 m0, s41
	s_nop 0
	global_load_lds_dwordx4 v[186:187], off
	ds_read_b128 v[186:189], v179 offset:32768
	ds_read_b128 v[190:193], v179 offset:33792
	ds_read_b128 v[194:197], v179 offset:34816
	ds_read_b128 v[198:201], v179 offset:35840
	ds_read_b128 v[202:205], v179 offset:36864
	ds_read_b128 v[206:209], v179 offset:37888
	ds_read_b128 v[210:213], v179 offset:38912
	ds_read_b128 v[214:217], v179 offset:39936
	s_waitcnt vmcnt(8)
	s_waitcnt lgkmcnt(0)
	s_barrier
	s_waitcnt lgkmcnt(0)
	v_mfma_f32_16x16x32_bf16 v[124:127], v[128:131], v[186:189], v[124:127]
	v_mfma_f32_16x16x32_bf16 v[124:127], v[132:135], v[190:193], v[124:127]
	v_mfma_f32_16x16x32_bf16 v[120:123], v[136:139], v[186:189], v[120:123]
	v_mfma_f32_16x16x32_bf16 v[120:123], v[140:143], v[190:193], v[120:123]
	v_mfma_f32_16x16x32_bf16 v[108:111], v[128:131], v[194:197], v[108:111]
	v_mfma_f32_16x16x32_bf16 v[108:111], v[132:135], v[198:201], v[108:111]
	v_mfma_f32_16x16x32_bf16 v[104:107], v[136:139], v[194:197], v[104:107]
	v_mfma_f32_16x16x32_bf16 v[104:107], v[140:143], v[198:201], v[104:107]
	v_mfma_f32_16x16x32_bf16 v[92:95], v[128:131], v[202:205], v[92:95]
	v_mfma_f32_16x16x32_bf16 v[92:95], v[132:135], v[206:209], v[92:95]
	v_mfma_f32_16x16x32_bf16 v[88:91], v[136:139], v[202:205], v[88:91]
	v_mfma_f32_16x16x32_bf16 v[88:91], v[140:143], v[206:209], v[88:91]
	v_mfma_f32_16x16x32_bf16 v[76:79], v[128:131], v[210:213], v[76:79]
	v_mfma_f32_16x16x32_bf16 v[76:79], v[132:135], v[214:217], v[76:79]
	v_mfma_f32_16x16x32_bf16 v[72:75], v[136:139], v[210:213], v[72:75]
	v_mfma_f32_16x16x32_bf16 v[72:75], v[140:143], v[214:217], v[72:75]
	v_mfma_f32_16x16x32_bf16 v[116:119], v[144:147], v[186:189], v[116:119]
	v_mfma_f32_16x16x32_bf16 v[116:119], v[148:151], v[190:193], v[116:119]
	v_mfma_f32_16x16x32_bf16 v[112:115], v[170:173], v[186:189], v[112:115]
	v_mfma_f32_16x16x32_bf16 v[112:115], v[182:185], v[190:193], v[112:115]
	v_mfma_f32_16x16x32_bf16 v[100:103], v[144:147], v[194:197], v[100:103]
	v_mfma_f32_16x16x32_bf16 v[100:103], v[148:151], v[198:201], v[100:103]
	v_mfma_f32_16x16x32_bf16 v[96:99], v[170:173], v[194:197], v[96:99]
	v_mfma_f32_16x16x32_bf16 v[96:99], v[182:185], v[198:201], v[96:99]
	v_mfma_f32_16x16x32_bf16 v[84:87], v[144:147], v[202:205], v[84:87]
	v_mfma_f32_16x16x32_bf16 v[84:87], v[148:151], v[206:209], v[84:87]
	v_mfma_f32_16x16x32_bf16 v[80:83], v[170:173], v[202:205], v[80:83]
	v_mfma_f32_16x16x32_bf16 v[80:83], v[182:185], v[206:209], v[80:83]
	v_mfma_f32_16x16x32_bf16 v[68:71], v[144:147], v[210:213], v[68:71]
	v_mfma_f32_16x16x32_bf16 v[68:71], v[148:151], v[214:217], v[68:71]
	v_mfma_f32_16x16x32_bf16 v[64:67], v[170:173], v[210:213], v[64:67]
	v_mfma_f32_16x16x32_bf16 v[64:67], v[182:185], v[214:217], v[64:67]
	s_barrier
	s_add_i32 s26, s58, s37
	v_lshl_add_u64 v[186:187], v[218:219], 0, s[14:15]
	s_mov_b32 m0, s26
	s_nop 0
	global_load_lds_dwordx4 v[186:187], off
	s_add_i32 m0, s26, 0x2000
	s_add_u32 s24, s24, 0x400800
	v_lshl_add_u64 v[186:187], v[220:221], 0, s[14:15]
	s_addc_u32 s25, s25, 0
	s_add_i32 s26, s59, s37
	global_load_lds_dwordx4 v[186:187], off
	v_lshl_add_u64 v[186:187], s[24:25], 0, v[154:155]
	s_mov_b32 m0, s26
	s_nop 0
	global_load_lds_dwordx4 v[186:187], off
	v_lshl_add_u64 v[186:187], s[24:25], 0, v[158:159]
	s_add_i32 m0, s26, 0x2000
	s_nop 0
	global_load_lds_dwordx4 v[186:187], off
	v_lshl_add_u64 v[186:187], v[222:223], 0, s[14:15]
	s_mov_b32 m0, s43
	s_nop 0
	global_load_lds_dwordx4 v[186:187], off
	v_lshl_add_u64 v[186:187], v[224:225], 0, s[14:15]
	s_mov_b32 m0, s44
	s_nop 0
	global_load_lds_dwordx4 v[186:187], off
	ds_read_b128 v[186:189], v179 offset:49152
	ds_read_b128 v[190:193], v179 offset:50176
	ds_read_b128 v[194:197], v179 offset:51200
	ds_read_b128 v[198:201], v179 offset:52224
	ds_read_b128 v[202:205], v179 offset:53248
	ds_read_b128 v[206:209], v179 offset:54272
	ds_read_b128 v[210:213], v179 offset:55296
	ds_read_b128 v[214:217], v179 offset:56320
	s_waitcnt vmcnt(8)
	s_waitcnt lgkmcnt(0)
	s_barrier
	s_waitcnt lgkmcnt(0)
	v_mfma_f32_16x16x32_bf16 v[60:63], v[128:131], v[186:189], v[60:63]
	v_mfma_f32_16x16x32_bf16 v[60:63], v[132:135], v[190:193], v[60:63]
	v_mfma_f32_16x16x32_bf16 v[56:59], v[136:139], v[186:189], v[56:59]
	v_mfma_f32_16x16x32_bf16 v[56:59], v[140:143], v[190:193], v[56:59]
	v_mfma_f32_16x16x32_bf16 v[44:47], v[128:131], v[194:197], v[44:47]
	v_mfma_f32_16x16x32_bf16 v[44:47], v[132:135], v[198:201], v[44:47]
	v_mfma_f32_16x16x32_bf16 v[40:43], v[136:139], v[194:197], v[40:43]
	v_mfma_f32_16x16x32_bf16 v[40:43], v[140:143], v[198:201], v[40:43]
	v_mfma_f32_16x16x32_bf16 v[28:31], v[128:131], v[202:205], v[28:31]
	v_mfma_f32_16x16x32_bf16 v[28:31], v[132:135], v[206:209], v[28:31]
	v_mfma_f32_16x16x32_bf16 v[24:27], v[136:139], v[202:205], v[24:27]
	v_mfma_f32_16x16x32_bf16 v[24:27], v[140:143], v[206:209], v[24:27]
	v_mfma_f32_16x16x32_bf16 v[12:15], v[128:131], v[210:213], v[12:15]
	v_mfma_f32_16x16x32_bf16 v[12:15], v[132:135], v[214:217], v[12:15]
	v_mfma_f32_16x16x32_bf16 v[8:11], v[136:139], v[210:213], v[8:11]
	v_mfma_f32_16x16x32_bf16 v[8:11], v[140:143], v[214:217], v[8:11]
	v_mfma_f32_16x16x32_bf16 v[52:55], v[144:147], v[186:189], v[52:55]
	v_mfma_f32_16x16x32_bf16 v[52:55], v[148:151], v[190:193], v[52:55]
	v_mfma_f32_16x16x32_bf16 v[48:51], v[170:173], v[186:189], v[48:51]
	v_mfma_f32_16x16x32_bf16 v[48:51], v[182:185], v[190:193], v[48:51]
	v_mfma_f32_16x16x32_bf16 v[36:39], v[144:147], v[194:197], v[36:39]
	v_mfma_f32_16x16x32_bf16 v[36:39], v[148:151], v[198:201], v[36:39]
	v_mfma_f32_16x16x32_bf16 v[32:35], v[170:173], v[194:197], v[32:35]
	v_mfma_f32_16x16x32_bf16 v[32:35], v[182:185], v[198:201], v[32:35]
	v_mfma_f32_16x16x32_bf16 v[20:23], v[144:147], v[202:205], v[20:23]
	v_mfma_f32_16x16x32_bf16 v[20:23], v[148:151], v[206:209], v[20:23]
	v_mfma_f32_16x16x32_bf16 v[16:19], v[170:173], v[202:205], v[16:19]
	v_mfma_f32_16x16x32_bf16 v[16:19], v[182:185], v[206:209], v[16:19]
	v_mfma_f32_16x16x32_bf16 v[4:7], v[144:147], v[210:213], v[4:7]
	v_mfma_f32_16x16x32_bf16 v[4:7], v[148:151], v[214:217], v[4:7]
	v_mfma_f32_16x16x32_bf16 v[0:3], v[170:173], v[210:213], v[0:3]
	v_mfma_f32_16x16x32_bf16 v[0:3], v[182:185], v[214:217], v[0:3]
	s_barrier
	s_add_i32 s57, s57, 2
	s_add_u32 s22, s22, 0x1000
	s_addc_u32 s23, s23, 0
	s_add_u32 s55, s55, 0x1000
	s_addc_u32 s56, s56, 0
	s_cmpk_gt_u32 s57, 0xfd
	s_cbranch_scc0 .LBB0_1625
	s_and_b64 vcc, exec, s[6:7]
	s_cbranch_vccz .LBB0_1628
	s_barrier
